# code placement: 64-byte alignment before the 4 attention main-loop heads and the 8 GEMM K-loop heads; on top of v18
# baseline (speedup 1.0000x reference)
; #define PG8_BAR __builtin_amdgcn_s_barrier()
; template <class Epi, bool ALIGN_EPI = true, bool BLOCKDIAG = false>
; __device__ __forceinline__ void gemm_phase(PG8_LAS unsigned char* lds, const Gemm g, const StaticOrder& S, const Epi& E) {
;     ...
;         const bool has_next = S.next(ui + 1, nxt);
;         const char* nA = has_next ? (const char*)g.A + (size_t)nxt.pm * tstepA : cA; const char* nB = has_next ? (const char*)g.Bt + (size_t)nxt.pn * tstepB : cB;
;         if constexpr (BLOCKDIAG) { PG8_KLOOP(0, nt / 2, 0) PG8_KLOOP(nt / 2, nt, 1) } else { PG8_KLOOP(0, nt, 2) }
;         if constexpr (ALIGN_EPI) { if (wr == 0) PG8_BAR; }
;         E(acc, cur, wr, wc, fr, fq);
;         if (!has_next) break;
; #pragma unroll
;         for (int a = 0; a < 2; ++a)
; #pragma unroll
;             for (int b = 0; b < 2; ++b)
; #pragma unroll
;                 for (int m = 0; m < 4; ++m)
; #pragma unroll
;                     for (int n = 0; n < 2; ++n) acc[a][b][m][n] = (f32x4){0.f, 0.f, 0.f, 0.f};
.LBB0_226:
	s_ashr_i32 s15, s14, 31
	s_lshl_b64 s[16:17], s[14:15], 19
	s_add_u32 s86, s72, s16
	s_addc_u32 s87, s73, s17
	s_and_b64 s[16:17], s[4:5], exec
	s_cselect_b32 s15, s87, s93
	s_cselect_b32 s16, s86, s92
	s_ashr_i32 s13, s12, 31
	s_lshl_b64 s[56:57], s[12:13], 19
	s_add_u32 s88, s6, s56
	s_addc_u32 s89, s7, s57
	s_and_b64 s[56:57], s[4:5], exec
	s_cselect_b32 s13, s89, s95
	s_cselect_b32 s17, s88, s94
	s_add_u32 s92, s92, 0x40080
	s_addc_u32 s93, s93, 0
	s_add_u32 s56, s94, 0x100
	v_mov_b32_e32 v0, 0
	s_addc_u32 s57, s95, 0
	s_mov_b32 s58, -2
	v_mov_b32_e32 v1, v0
	v_mov_b32_e32 v2, v0
	v_mov_b32_e32 v3, v0
	v_mov_b32_e32 v8, v0
	v_mov_b32_e32 v9, v0
	v_mov_b32_e32 v10, v0
	v_mov_b32_e32 v11, v0
	v_mov_b32_e32 v16, v0
	v_mov_b32_e32 v17, v0
	v_mov_b32_e32 v18, v0
	v_mov_b32_e32 v19, v0
	v_mov_b32_e32 v24, v0
	v_mov_b32_e32 v25, v0
	v_mov_b32_e32 v26, v0
	v_mov_b32_e32 v27, v0
	v_mov_b32_e32 v32, v0
	v_mov_b32_e32 v33, v0
	v_mov_b32_e32 v34, v0
	v_mov_b32_e32 v35, v0
	v_mov_b32_e32 v40, v0
	v_mov_b32_e32 v41, v0
	v_mov_b32_e32 v42, v0
	v_mov_b32_e32 v43, v0
	v_mov_b32_e32 v48, v0
	v_mov_b32_e32 v49, v0
	v_mov_b32_e32 v50, v0
	v_mov_b32_e32 v51, v0
	v_mov_b32_e32 v56, v0
	v_mov_b32_e32 v57, v0
	v_mov_b32_e32 v58, v0
	v_mov_b32_e32 v59, v0
	v_mov_b32_e32 v4, v0
	v_mov_b32_e32 v5, v0
	v_mov_b32_e32 v6, v0
	v_mov_b32_e32 v7, v0
	v_mov_b32_e32 v12, v0
	v_mov_b32_e32 v13, v0
	v_mov_b32_e32 v14, v0
	v_mov_b32_e32 v15, v0
	v_mov_b32_e32 v20, v0
	v_mov_b32_e32 v21, v0
	v_mov_b32_e32 v22, v0
	v_mov_b32_e32 v23, v0
	v_mov_b32_e32 v28, v0
	v_mov_b32_e32 v29, v0
	v_mov_b32_e32 v30, v0
	v_mov_b32_e32 v31, v0
	v_mov_b32_e32 v36, v0
	v_mov_b32_e32 v37, v0
	v_mov_b32_e32 v38, v0
	v_mov_b32_e32 v39, v0
	v_mov_b32_e32 v44, v0
	v_mov_b32_e32 v45, v0
	v_mov_b32_e32 v46, v0
	v_mov_b32_e32 v47, v0
	v_mov_b32_e32 v52, v0
	v_mov_b32_e32 v53, v0
	v_mov_b32_e32 v54, v0
	v_mov_b32_e32 v55, v0
	v_mov_b32_e32 v60, v0
	v_mov_b32_e32 v61, v0
	v_mov_b32_e32 v62, v0
	v_mov_b32_e32 v63, v0
	v_mov_b32_e32 v64, v0
	v_mov_b32_e32 v65, v0
	v_mov_b32_e32 v66, v0
	v_mov_b32_e32 v67, v0
	v_mov_b32_e32 v72, v0
	v_mov_b32_e32 v73, v0
	v_mov_b32_e32 v74, v0
	v_mov_b32_e32 v75, v0
	v_mov_b32_e32 v80, v0
	v_mov_b32_e32 v81, v0
	v_mov_b32_e32 v82, v0
	v_mov_b32_e32 v83, v0
	v_mov_b32_e32 v88, v0
	v_mov_b32_e32 v89, v0
	v_mov_b32_e32 v90, v0
	v_mov_b32_e32 v91, v0
	v_mov_b32_e32 v96, v0
	v_mov_b32_e32 v97, v0
	v_mov_b32_e32 v98, v0
	v_mov_b32_e32 v99, v0
	v_mov_b32_e32 v104, v0
	v_mov_b32_e32 v105, v0
	v_mov_b32_e32 v106, v0
	v_mov_b32_e32 v107, v0
	v_mov_b32_e32 v112, v0
	v_mov_b32_e32 v113, v0
	v_mov_b32_e32 v114, v0
	v_mov_b32_e32 v115, v0
	v_mov_b32_e32 v120, v0
	v_mov_b32_e32 v121, v0
	v_mov_b32_e32 v122, v0
	v_mov_b32_e32 v123, v0
	v_mov_b32_e32 v68, v0
	v_mov_b32_e32 v69, v0
	v_mov_b32_e32 v70, v0
	v_mov_b32_e32 v71, v0
	v_mov_b32_e32 v76, v0
	v_mov_b32_e32 v77, v0
	v_mov_b32_e32 v78, v0
	v_mov_b32_e32 v79, v0
	v_mov_b32_e32 v84, v0
	v_mov_b32_e32 v85, v0
	v_mov_b32_e32 v86, v0
	v_mov_b32_e32 v87, v0
	v_mov_b32_e32 v92, v0
	v_mov_b32_e32 v93, v0
	v_mov_b32_e32 v94, v0
	v_mov_b32_e32 v95, v0
	v_mov_b32_e32 v100, v0
	v_mov_b32_e32 v101, v0
	v_mov_b32_e32 v102, v0
	v_mov_b32_e32 v103, v0
	v_mov_b32_e32 v108, v0
	v_mov_b32_e32 v109, v0
	v_mov_b32_e32 v110, v0
	v_mov_b32_e32 v111, v0
	v_mov_b32_e32 v116, v0
	v_mov_b32_e32 v117, v0
	v_mov_b32_e32 v118, v0
	v_mov_b32_e32 v119, v0
	v_mov_b32_e32 v124, v0
	v_mov_b32_e32 v125, v0
	v_mov_b32_e32 v126, v0
	v_mov_b32_e32 v127, v0
	.p2align	6

; template <class Epi, bool ALIGN_EPI = true, bool BLOCKDIAG = false>
; __device__ __forceinline__ void gemm_phase(PG8_LAS unsigned char* lds, const Gemm g, const StaticOrder& S, const Epi& E) {
;     ...
; #pragma unroll
;         for (int a = 0; a < 2; ++a)
; #pragma unroll
;             for (int b = 0; b < 2; ++b)
; #pragma unroll
;                 for (int m = 0; m < 4; ++m)
; #pragma unroll
;                     for (int n = 0; n < 2; ++n) acc[a][b][m][n] = (f32x4){0.f, 0.f, 0.f, 0.f};
;         cur = nxt; cA = nA; cB = nB; ++ui;
.LBB0_380:
	s_add_u32 s17, s44, 0x100
	v_mov_b32_e32 v0, 0
	s_addc_u32 s34, s45, 0
	s_mov_b32 s35, -2
	s_waitcnt lgkmcnt(0)
	v_mov_b32_e32 v1, v0
	v_mov_b32_e32 v2, v0
	v_mov_b32_e32 v3, v0
	v_mov_b32_e32 v4, v0
	v_mov_b32_e32 v5, v0
	v_mov_b32_e32 v6, v0
	v_mov_b32_e32 v7, v0
	v_mov_b32_e32 v16, v0
	v_mov_b32_e32 v17, v0
	v_mov_b32_e32 v18, v0
	v_mov_b32_e32 v19, v0
	v_mov_b32_e32 v20, v0
	v_mov_b32_e32 v21, v0
	v_mov_b32_e32 v22, v0
	v_mov_b32_e32 v23, v0
	v_mov_b32_e32 v32, v0
	v_mov_b32_e32 v33, v0
	v_mov_b32_e32 v34, v0
	v_mov_b32_e32 v35, v0
	v_mov_b32_e32 v36, v0
	v_mov_b32_e32 v37, v0
	v_mov_b32_e32 v38, v0
	v_mov_b32_e32 v39, v0
	v_mov_b32_e32 v48, v0
	v_mov_b32_e32 v49, v0
	v_mov_b32_e32 v50, v0
	v_mov_b32_e32 v51, v0
	v_mov_b32_e32 v52, v0
	v_mov_b32_e32 v53, v0
	v_mov_b32_e32 v54, v0
	v_mov_b32_e32 v55, v0
	v_mov_b32_e32 v8, v0
	v_mov_b32_e32 v9, v0
	v_mov_b32_e32 v10, v0
	v_mov_b32_e32 v11, v0
	v_mov_b32_e32 v12, v0
	v_mov_b32_e32 v13, v0
	v_mov_b32_e32 v14, v0
	v_mov_b32_e32 v15, v0
	v_mov_b32_e32 v24, v0
	v_mov_b32_e32 v25, v0
	v_mov_b32_e32 v26, v0
	v_mov_b32_e32 v27, v0
	v_mov_b32_e32 v28, v0
	v_mov_b32_e32 v29, v0
	v_mov_b32_e32 v30, v0
	v_mov_b32_e32 v31, v0
	v_mov_b32_e32 v40, v0
	v_mov_b32_e32 v41, v0
	v_mov_b32_e32 v42, v0
	v_mov_b32_e32 v43, v0
	v_mov_b32_e32 v44, v0
	v_mov_b32_e32 v45, v0
	v_mov_b32_e32 v46, v0
	v_mov_b32_e32 v47, v0
	v_mov_b32_e32 v64, v0
	v_mov_b32_e32 v65, v0
	v_mov_b32_e32 v66, v0
	v_mov_b32_e32 v67, v0
	v_mov_b32_e32 v76, v0
	v_mov_b32_e32 v77, v0
	v_mov_b32_e32 v78, v0
	v_mov_b32_e32 v79, v0
	v_mov_b32_e32 v80, v0
	v_mov_b32_e32 v81, v0
	v_mov_b32_e32 v82, v0
	v_mov_b32_e32 v83, v0
	v_mov_b32_e32 v84, v0
	v_mov_b32_e32 v85, v0
	v_mov_b32_e32 v86, v0
	v_mov_b32_e32 v87, v0
	v_mov_b32_e32 v96, v0
	v_mov_b32_e32 v97, v0
	v_mov_b32_e32 v98, v0
	v_mov_b32_e32 v99, v0
	v_mov_b32_e32 v100, v0
	v_mov_b32_e32 v101, v0
	v_mov_b32_e32 v102, v0
	v_mov_b32_e32 v103, v0
	v_mov_b32_e32 v112, v0
	v_mov_b32_e32 v113, v0
	v_mov_b32_e32 v114, v0
	v_mov_b32_e32 v115, v0
	v_mov_b32_e32 v116, v0
	v_mov_b32_e32 v117, v0
	v_mov_b32_e32 v118, v0
	v_mov_b32_e32 v119, v0
	v_mov_b32_e32 v128, v0
	v_mov_b32_e32 v129, v0
	v_mov_b32_e32 v130, v0
	v_mov_b32_e32 v131, v0
	v_mov_b32_e32 v132, v0
	v_mov_b32_e32 v133, v0
	v_mov_b32_e32 v134, v0
	v_mov_b32_e32 v135, v0
	v_mov_b32_e32 v88, v0
	v_mov_b32_e32 v89, v0
	v_mov_b32_e32 v90, v0
	v_mov_b32_e32 v91, v0
	v_mov_b32_e32 v92, v0
	v_mov_b32_e32 v93, v0
	v_mov_b32_e32 v94, v0
	v_mov_b32_e32 v95, v0
	v_mov_b32_e32 v104, v0
	v_mov_b32_e32 v105, v0
	v_mov_b32_e32 v106, v0
	v_mov_b32_e32 v107, v0
	v_mov_b32_e32 v108, v0
	v_mov_b32_e32 v109, v0
	v_mov_b32_e32 v110, v0
	v_mov_b32_e32 v111, v0
	v_mov_b32_e32 v120, v0
	v_mov_b32_e32 v121, v0
	v_mov_b32_e32 v122, v0
	v_mov_b32_e32 v123, v0
	v_mov_b32_e32 v124, v0
	v_mov_b32_e32 v125, v0
	v_mov_b32_e32 v126, v0
	v_mov_b32_e32 v127, v0
	v_mov_b32_e32 v136, v0
	v_mov_b32_e32 v137, v0
	v_mov_b32_e32 v138, v0
	v_mov_b32_e32 v139, v0
	v_mov_b32_e32 v140, v0
	v_mov_b32_e32 v141, v0
	v_mov_b32_e32 v142, v0
	v_mov_b32_e32 v143, v0
	.p2align	6

; #define PG8_BAR __builtin_amdgcn_s_barrier()
; template <class Epi, bool ALIGN_EPI = true, bool BLOCKDIAG = false>
; __device__ __forceinline__ void gemm_phase(PG8_LAS unsigned char* lds, const Gemm g, const StaticOrder& S, const Epi& E) {
;     ...
;         const bool has_next = S.next(ui + 1, nxt);
;         const char* nA = has_next ? (const char*)g.A + (size_t)nxt.pm * tstepA : cA; const char* nB = has_next ? (const char*)g.Bt + (size_t)nxt.pn * tstepB : cB;
;         if constexpr (BLOCKDIAG) { PG8_KLOOP(0, nt / 2, 0) PG8_KLOOP(nt / 2, nt, 1) } else { PG8_KLOOP(0, nt, 2) }
;         if constexpr (ALIGN_EPI) { if (wr == 0) PG8_BAR; }
;         E(acc, cur, wr, wc, fr, fq);
;         if (!has_next) break;
; #pragma unroll
;         for (int a = 0; a < 2; ++a)
; #pragma unroll
;             for (int b = 0; b < 2; ++b)
; #pragma unroll
;                 for (int m = 0; m < 4; ++m)
; #pragma unroll
;                     for (int n = 0; n < 2; ++n) acc[a][b][m][n] = (f32x4){0.f, 0.f, 0.f, 0.f};
.LBB0_498:
	s_ashr_i32 s69, s68, 31
	s_lshl_b64 s[16:17], s[68:69], 19
	s_add_u32 s70, s72, s16
	s_addc_u32 s71, s73, s17
	s_and_b64 s[16:17], s[10:11], exec
	s_cselect_b32 s1, s71, s15
	s_cselect_b32 s13, s70, s14
	s_ashr_i32 s5, s4, 31
	s_lshl_b64 s[16:17], s[4:5], 19
	s_add_u32 s74, s3, s16
	s_addc_u32 s75, s80, s17
	s_and_b64 s[16:17], s[10:11], exec
	s_cselect_b32 s16, s75, s77
	s_cselect_b32 s17, s74, s76
	s_add_u32 s14, s14, 0x40080
	s_addc_u32 s15, s15, 0
	s_add_u32 s18, s76, 0x100
	v_mov_b32_e32 v8, 0
	s_addc_u32 s19, s77, 0
	s_mov_b32 s28, -2
	v_mov_b32_e32 v9, v8
	v_mov_b32_e32 v10, v8
	v_mov_b32_e32 v11, v8
	v_mov_b32_e32 v12, v8
	v_mov_b32_e32 v13, v8
	v_mov_b32_e32 v14, v8
	v_mov_b32_e32 v15, v8
	v_mov_b32_e32 v40, v8
	v_mov_b32_e32 v41, v8
	v_mov_b32_e32 v42, v8
	v_mov_b32_e32 v43, v8
	v_mov_b32_e32 v48, v8
	v_mov_b32_e32 v49, v8
	v_mov_b32_e32 v50, v8
	v_mov_b32_e32 v51, v8
	v_mov_b32_e32 v56, v8
	v_mov_b32_e32 v57, v8
	v_mov_b32_e32 v58, v8
	v_mov_b32_e32 v59, v8
	v_mov_b32_e32 v64, v8
	v_mov_b32_e32 v65, v8
	v_mov_b32_e32 v66, v8
	v_mov_b32_e32 v67, v8
	v_mov_b32_e32 v72, v8
	v_mov_b32_e32 v73, v8
	v_mov_b32_e32 v74, v8
	v_mov_b32_e32 v75, v8
	v_mov_b32_e32 v80, v8
	v_mov_b32_e32 v81, v8
	v_mov_b32_e32 v82, v8
	v_mov_b32_e32 v83, v8
	v_mov_b32_e32 v16, v8
	v_mov_b32_e32 v17, v8
	v_mov_b32_e32 v18, v8
	v_mov_b32_e32 v19, v8
	s_waitcnt vmcnt(0)
	v_mov_b32_e32 v20, v8
	v_mov_b32_e32 v21, v8
	v_mov_b32_e32 v22, v8
	v_mov_b32_e32 v23, v8
	v_mov_b32_e32 v44, v8
	v_mov_b32_e32 v45, v8
	v_mov_b32_e32 v46, v8
	v_mov_b32_e32 v47, v8
	v_mov_b32_e32 v52, v8
	v_mov_b32_e32 v53, v8
	v_mov_b32_e32 v54, v8
	v_mov_b32_e32 v55, v8
	v_mov_b32_e32 v60, v8
	v_mov_b32_e32 v61, v8
	v_mov_b32_e32 v62, v8
	v_mov_b32_e32 v63, v8
	v_mov_b32_e32 v68, v8
	v_mov_b32_e32 v69, v8
	v_mov_b32_e32 v70, v8
	v_mov_b32_e32 v71, v8
	v_mov_b32_e32 v76, v8
	v_mov_b32_e32 v77, v8
	v_mov_b32_e32 v78, v8
	v_mov_b32_e32 v79, v8
	v_mov_b32_e32 v84, v8
	v_mov_b32_e32 v85, v8
	v_mov_b32_e32 v86, v8
	v_mov_b32_e32 v87, v8
	v_mov_b32_e32 v88, v8
	v_mov_b32_e32 v89, v8
	v_mov_b32_e32 v90, v8
	v_mov_b32_e32 v91, v8
	v_mov_b32_e32 v96, v8
	v_mov_b32_e32 v97, v8
	v_mov_b32_e32 v98, v8
	v_mov_b32_e32 v99, v8
	v_mov_b32_e32 v104, v8
	v_mov_b32_e32 v105, v8
	v_mov_b32_e32 v106, v8
	v_mov_b32_e32 v107, v8
	v_mov_b32_e32 v112, v8
	v_mov_b32_e32 v113, v8
	v_mov_b32_e32 v114, v8
	v_mov_b32_e32 v115, v8
	v_mov_b32_e32 v120, v8
	v_mov_b32_e32 v121, v8
	v_mov_b32_e32 v122, v8
	v_mov_b32_e32 v123, v8
	v_mov_b32_e32 v124, v8
	v_mov_b32_e32 v125, v8
	v_mov_b32_e32 v126, v8
	v_mov_b32_e32 v127, v8
	v_mov_b32_e32 v0, v8
	v_mov_b32_e32 v1, v8
	v_mov_b32_e32 v2, v8
	v_mov_b32_e32 v3, v8
	v_mov_b32_e32 v4, v8
	v_mov_b32_e32 v5, v8
	v_mov_b32_e32 v6, v8
	v_mov_b32_e32 v7, v8
	v_mov_b32_e32 v92, v8
	v_mov_b32_e32 v93, v8
	v_mov_b32_e32 v94, v8
	v_mov_b32_e32 v95, v8
	v_mov_b32_e32 v100, v8
	v_mov_b32_e32 v101, v8
	v_mov_b32_e32 v102, v8
	v_mov_b32_e32 v103, v8
	v_mov_b32_e32 v108, v8
	v_mov_b32_e32 v109, v8
	v_mov_b32_e32 v110, v8
	v_mov_b32_e32 v111, v8
	v_mov_b32_e32 v116, v8
	v_mov_b32_e32 v117, v8
	v_mov_b32_e32 v118, v8
	v_mov_b32_e32 v119, v8
	v_mov_b32_e32 v128, v8
	v_mov_b32_e32 v129, v8
	v_mov_b32_e32 v130, v8
	v_mov_b32_e32 v131, v8
	v_mov_b32_e32 v132, v8
	v_mov_b32_e32 v133, v8
	v_mov_b32_e32 v134, v8
	v_mov_b32_e32 v135, v8
	v_mov_b32_e32 v136, v8
	v_mov_b32_e32 v137, v8
	v_mov_b32_e32 v138, v8
	v_mov_b32_e32 v139, v8
	v_mov_b32_e32 v140, v8
	v_mov_b32_e32 v141, v8
	v_mov_b32_e32 v142, v8
	v_mov_b32_e32 v143, v8
	.p2align	6

; #define WAIT_BAR(N) asm volatile("s_waitcnt vmcnt(" #N ") lgkmcnt(0)\n\ts_barrier":::"memory")
;   #define DMA_K(t,slot) glds16(ksrc+(long)(t)*KVBLK*KVP,(unsigned)__builtin_amdgcn_readfirstlane(kdst+(slot)))
;   #define DMA_V(t,slot) do{ glds16(vsrc+(long)(t)*KVBLK*KVP,(unsigned)__builtin_amdgcn_readfirstlane(vdst+VM*(slot))); if constexpr(VM==2) glds16(vsrc+64+(long)(t)*KVBLK*KVP,(unsigned)__builtin_amdgcn_readfirstlane(vdst+VM*(slot)+8192)); }while(0)
; template<int THRL,int VM,bool NOMAX> __device__ __forceinline__ void attn_unit(const bf16*Qb,const bf16*__restrict__ Kh,const bf16*__restrict__ Vh,bf16*Ob,const int NT,const int sp,float*wscr,char*shm){
;   int tid_=threadIdx.x; asm volatile("":"+v"(tid_));
;   const int tid=tid_,lane=tid&63,r32=lane&31,hi=lane>>5; const int wid=__builtin_amdgcn_readfirstlane(tid>>6);
;   const bf16*Qw=Qb+(long)(wid*QBLK)*QOP;
;   const unsigned lds0=(unsigned)(uintptr_t)shm;
;   constexpr int LDS_WS_=LDS_V+3*VM*SLOTB, LDS_OST_=LDS_WS_+NW*64*4;
;   float*wsf=(float*)(shm+LDS_WS_)+wid*64;
;   const bf16*ksrc=Kh+(long)lane*KVP+wid*8;
;   const bf16*vsrc=Vh+(long)(16*(wid&3)+(lane>>2))*KVP+(wid>>2)*32+(lane&3)*8;
;   const unsigned kdst=lds0+LDS_K+wid*1024, vdst=lds0+LDS_V+wid*1024;
;     ...
;   const int vb0=(int)(lds0+LDS_V)+((lane>>4)&1)*32+(lane&3)*8+(4*hi+((lane&15)>>2))*64;
;   const char*Kbase=shm+LDS_K; bf16x8 kf[8];
;   const lds_cptr shm3=(lds_cptr)shm; const lds_cptr kp0=shm3+LDS_K+hi*1024+r32*16; const lds_cptr vp0=shm3+LDS_V+((lane>>4)&1)*32+(lane&3)*8+(4*hi+((lane&15)>>2))*64;
;   if(wid>=4)__builtin_amdgcn_s_setprio(1);
;   DMA_K(0,0);DMA_V(0,0);DMA_K(1,SLOTB);
;   bf16x8 qr[4];
;   #pragma unroll
;   for(int d0=0;d0<4;++d0)qr[d0]=*reinterpret_cast<const bf16x8*>(&Qw[(long)r32*QOP+d0*16+hi*8]);
;   const lds_cptr qpk=shm3+LDS_OST_+wid*4096+lane*16;
;   if constexpr(VM==2){
;     #pragma unroll
;     for(int d0=0;d0<4;++d0)*(__attribute__((address_space(3))) bf16x8*)(const_cast<__attribute__((address_space(3))) char*>(qpk)+d0*1024)=qr[d0]; }
;   float mhat=0.f,l_reg=0.f;f32x16 o[2*VM];
;   #pragma unroll
;   for(int d_=0;d_<2*VM;++d_)o[d_]=f32x16{};
;  f32x16 negm=f32x16{}; if constexpr(VM==1){asm volatile("":"+v"(negm));}
;   bool resc=false;
;     ...
;   f32x16 pA0,pA1,pB0,pB1;
;   int sl_prev=0,sl_cur=0,sl_next=SLOTB;
;     ...
;   DMA_K(2,2*SLOTB);
;   WAIT_BAR(3);
.LBB0_862:
	s_xor_b64 s[6:7], s[16:17], -1
	s_lshl_b32 s16, s8, 7
	s_add_u32 s35, s83, s16
	s_addc_u32 s88, s84, 0
	s_add_u32 s16, s0, s16
	s_addc_u32 s17, s1, 0
	s_lshl_b32 s86, s85, 5
	v_and_b32_e32 v187, 63, v32
	s_ashr_i32 s87, s86, 31
	s_lshl_b64 s[86:87], s[86:87], 11
	v_mul_u32_u24_e32 v0, 0x500, v187
	s_add_u32 s86, s35, s86
	v_lshlrev_b32_e32 v168, 1, v0
	s_addc_u32 s87, s88, s87
	v_lshl_add_u64 v[0:1], s[16:17], 0, v[168:169]
	s_lshl_b32 s16, s85, 3
	s_ashr_i32 s17, s16, 31
	v_lshl_add_u64 v[54:55], s[16:17], 1, v[0:1]
	v_and_b32_e32 v246, 63, v210
	v_lshrrev_b32_e32 v247, 6, v210
	v_lshrrev_b32_e32 v248, 3, v246
	v_lshl_add_u32 v248, v247, 3, v248
	v_and_b32_e32 v249, 1, v247
	v_lshrrev_b32_e32 v250, 4, v246
	v_lshl_or_b32 v249, v249, 2, v250
	v_and_b32_e32 v250, 7, v246
	v_xor_b32_e32 v250, v250, v249
	v_sub_u32_e32 v248, v248, v246
	v_mul_i32_i24_e32 v248, 0xa00, v248
	v_sub_u32_e32 v250, v250, v247
	v_lshl_add_u32 v248, v250, 4, v248
	v_ashrrev_i32_e32 v249, 31, v248
	v_lshl_add_u64 v[54:55], v[248:249], 0, v[54:55]
	s_mov_b64 s[16:17], 0x200
	v_lshl_add_u64 v[174:175], v[54:55], 0, s[16:17]
	s_lshl_b32 s16, s85, 4
	v_bfe_u32 v0, v32, 2, 4
	v_and_or_b32 v0, s16, 48, v0
	v_mul_u32_u24_e32 v0, 0x500, v0
	s_ashr_i32 s16, s34, 3
	v_lshlrev_b32_e32 v168, 1, v0
	s_andn2_b32 s16, s16, 31
	v_lshlrev_b32_e32 v2, 3, v32
	v_lshl_add_u64 v[0:1], s[0:1], 0, v[168:169]
	s_ashr_i32 s17, s16, 31
	v_and_b32_e32 v190, 24, v2
	v_lshl_add_u64 v[0:1], s[16:17], 1, v[0:1]
	v_lshlrev_b32_e32 v168, 1, v190
	v_lshl_add_u64 v[56:57], v[0:1], 0, v[168:169]
	s_mov_b64 s[16:17], 0x600
	v_lshl_add_u64 v[170:171], v[56:57], 0, s[16:17]
	s_lshl_b32 s17, s85, 10
	s_cmp_lg_u32 0, -1
	s_cselect_b32 s16, 0, 0
	s_add_i32 s35, s17, s16
	s_mov_b32 s88, m0
	s_mov_b32 m0, s35
	s_nop 0
	global_load_lds_dwordx4 v[174:175], off
	s_mov_b32 m0, s88
	s_add_i32 s16, s35, 0x6000
	s_mov_b32 s88, m0
	s_mov_b32 m0, s16
	s_nop 0
	global_load_lds_dwordx4 v[170:171], off
	s_mov_b32 m0, s88
	v_and_b32_e32 v186, 31, v32
	v_lshl_add_u64 v[172:173], v[56:57], 0, s[12:13]
	s_add_i32 s88, s35, 0x8000
	s_mov_b32 s89, m0
	s_mov_b32 m0, s88
	s_nop 0
	global_load_lds_dwordx4 v[172:173], off
	s_mov_b32 m0, s89
	v_lshl_add_u64 v[0:1], v[54:55], 0, s[14:15]
	v_bfe_u32 v185, v32, 5, 1
	s_add_i32 s88, s35, 0x2000
	s_mov_b32 s89, m0
	s_mov_b32 m0, s88
	s_nop 0
	global_load_lds_dwordx4 v[0:1], off
	s_mov_b32 m0, s89
	v_lshlrev_b32_e32 v0, 11, v186
	v_lshl_or_b32 v4, v185, 4, v0
	global_load_dwordx4 v[0:3], v4, s[86:87] offset:1024
	global_load_dwordx4 v[34:37], v4, s[86:87] offset:1056
	global_load_dwordx4 v[38:41], v4, s[86:87] offset:1088
	global_load_dwordx4 v[42:45], v4, s[86:87] offset:1120
	s_lshl_b32 s85, s85, 12
	s_add_i32 s85, s85, 0
	v_lshlrev_b32_e32 v6, 4, v187
	s_add_i32 s85, s85, 0x12800
	v_add_u32_e32 v188, s85, v6
	v_lshlrev_b32_e32 v4, 10, v185
	v_lshlrev_b32_e32 v5, 4, v186
	v_add3_u32 v189, 0, v4, v5
	v_bfe_u32 v246, v189, 4, 5
	v_bfe_u32 v247, v189, 10, 1
	v_bfe_u32 v248, v189, 5, 1
	v_bfe_u32 v249, v189, 6, 2
	v_xor_b32_e32 v247, v247, v248
	v_lshlrev_b32_e32 v246, 7, v246
	v_lshl_or_b32 v246, v247, 4, v246
	v_lshl_add_u32 v234, v249, 5, v246
	v_xor_b32_e32 v248, 1, v249
	v_lshl_add_u32 v235, v248, 5, v246
	v_xor_b32_e32 v248, 2, v249
	v_lshl_add_u32 v236, v248, 5, v246
	v_xor_b32_e32 v248, 3, v249
	v_lshl_add_u32 v237, v248, 5, v246
	v_lshl_add_u64 v[4:5], v[54:55], 0, s[36:37]
	s_add_i32 s86, s35, 0x4000
	v_lshlrev_b32_e32 v33, 1, v32
	v_lshlrev_b32_e32 v32, 4, v32
	v_and_b32_e32 v191, 32, v33
	v_and_b32_e32 v32, 0xc0, v32
	v_lshl_or_b32 v192, v185, 8, v32
	v_add_u32_e32 v32, 0, v191
	v_add3_u32 v168, v32, v190, v192
	v_lshl_add_u64 v[32:33], v[54:55], 0, s[40:41]
	s_add_i32 s88, s35, 0xa000
	s_add_i32 s90, s35, 0xc000
	v_mov_b32_e32 v193, 0
	s_mov_b32 s89, 0
	s_movk_i32 s87, 0x2000
	v_lshl_add_u64 v[176:177], v[56:57], 0, s[48:49]
	v_lshl_add_u64 v[178:179], v[56:57], 0, s[50:51]
	v_lshl_add_u64 v[180:181], v[54:55], 0, s[52:53]
	v_mov_b32_e32 v54, v193
	v_mov_b32_e32 v55, v193
	v_mov_b32_e32 v58, v193
	v_mov_b32_e32 v59, v193
	v_mov_b32_e32 v60, v193
	v_mov_b32_e32 v61, v193
	v_mov_b32_e32 v62, v193
	v_mov_b32_e32 v63, v193
	s_waitcnt vmcnt(3)
	ds_write_b128 v188, v[0:3]
	s_waitcnt vmcnt(2)
	ds_write_b128 v188, v[34:37] offset:1024
	s_waitcnt vmcnt(1)
	ds_write_b128 v188, v[38:41] offset:2048
	s_waitcnt vmcnt(0)
	ds_write_b128 v188, v[42:45] offset:3072
	s_mov_b32 s85, m0
	s_mov_b32 m0, s86
	s_nop 0
	global_load_lds_dwordx4 v[4:5], off
	s_mov_b32 m0, s85
	s_waitcnt vmcnt(3) lgkmcnt(0)
	s_barrier
; #define WAIT_BAR(N) asm volatile("s_waitcnt vmcnt(" #N ") lgkmcnt(0)\n\ts_barrier":::"memory")
;   #define DMA_K(t,slot) glds16(ksrc+(long)(t)*KVBLK*KVP,(unsigned)__builtin_amdgcn_readfirstlane(kdst+(slot)))
;   #define DMA_V(t,slot) do{ glds16(vsrc+(long)(t)*KVBLK*KVP,(unsigned)__builtin_amdgcn_readfirstlane(vdst+VM*(slot))); if constexpr(VM==2) glds16(vsrc+64+(long)(t)*KVBLK*KVP,(unsigned)__builtin_amdgcn_readfirstlane(vdst+VM*(slot)+8192)); }while(0)
;   #define ROT() do{sl_prev=sl_cur;sl_cur=sl_next;sl_next=(sl_next==(NSLOT-1)*SLOTB)?0:sl_next+SLOTB;}while(0)
; template<int THRL,int VM,bool NOMAX> __device__ __forceinline__ void attn_unit(const bf16*Qb,const bf16*__restrict__ Kh,const bf16*__restrict__ Vh,bf16*Ob,const int NT,const int sp,float*wscr,char*shm){
;     ...
;   float mhat=0.f,l_reg=0.f;f32x16 o[2*VM];
;   #pragma unroll
;   for(int d_=0;d_<2*VM;++d_)o[d_]=f32x16{};
;     ...
;   DMA_K(2,2*SLOTB);
;   WAIT_BAR(3);
;   qkt(pA0,pA1,Kbase,qr,negm,r32,hi);asm volatile("s_nop 15\n\ts_nop 7":"+v"(pA0),"+v"(pA1));
;   START(pA0,pA1);
;   _Pragma("unroll") for(int r=0;r<16;++r)pA1[r]=__builtin_amdgcn_exp2f(pA1[r]);
;   WAIT_BAR(0);
;   DMA_K(3,0);DMA_V(1,SLOTB);
;   ROT();
;   kload8(kf,kp0+sl_cur);
;   if constexpr(VM==2){WAIT_BAR(3);}else{WAIT_BAR(2);}
	ds_read_b128 v[4:7], v234
	ds_read_b128 v[8:11], v234 offset:4096
	s_waitcnt lgkmcnt(1)
	v_mfma_f32_32x32x16_bf16 v[16:31], v[4:7], v[0:3], 0
	ds_read_b128 v[46:49], v235
	ds_read_b128 v[50:53], v235 offset:4096
	s_mov_b32 s85, -1
	s_movk_i32 s86, 0x4000
	s_waitcnt lgkmcnt(2)
	v_mfma_f32_32x32x16_bf16 v[0:15], v[8:11], v[0:3], 0
	s_waitcnt lgkmcnt(1)
	v_mfma_f32_32x32x16_bf16 v[16:31], v[46:49], v[34:37], v[16:31]
	s_waitcnt lgkmcnt(0)
	v_mfma_f32_32x32x16_bf16 v[0:15], v[50:53], v[34:37], v[0:15]
	ds_read_b128 v[34:37], v236
	ds_read_b128 v[46:49], v236 offset:4096
	s_waitcnt lgkmcnt(1)
	v_mfma_f32_32x32x16_bf16 v[16:31], v[34:37], v[38:41], v[16:31]
	ds_read_b128 v[34:37], v237 offset:4096
	ds_read_b128 v[50:53], v237
	s_waitcnt lgkmcnt(2)
	v_mfma_f32_32x32x16_bf16 v[0:15], v[46:49], v[38:41], v[0:15]
	v_lshl_add_u64 v[38:39], v[56:57], 0, s[42:43]
	v_lshl_add_u64 v[40:41], v[56:57], 0, s[44:45]
	v_mov_b32_e32 v48, 0
	v_mov_b32_e32 v49, v193
	v_mov_b32_e32 v56, v193
	v_mov_b32_e32 v57, v193
	v_mov_b32_e32 v46, v193
	s_waitcnt lgkmcnt(0)
	v_mfma_f32_32x32x16_bf16 v[16:31], v[50:53], v[42:45], v[16:31]
	v_mov_b32_e32 v50, v193
	v_mov_b32_e32 v51, v193
	v_mov_b32_e32 v52, v193
	v_mov_b32_e32 v53, v193
	v_mov_b32_e32 v47, v193
	v_mfma_f32_32x32x16_bf16 v[0:15], v[34:37], v[42:45], v[0:15]
	s_nop 15
	s_nop 7
	s_waitcnt vmcnt(0) lgkmcnt(0)
	s_barrier
	s_mov_b32 s91, m0
	s_mov_b32 m0, s35
	s_nop 0
	global_load_lds_dwordx4 v[32:33], off
	s_mov_b32 m0, s91
	v_mov_b32_e32 v32, 0
	s_mov_b32 s91, m0
	s_mov_b32 m0, s88
	s_nop 0
	global_load_lds_dwordx4 v[38:39], off
	s_mov_b32 m0, s91
	s_mov_b32 s88, m0
	s_mov_b32 m0, s90
	s_nop 0
	global_load_lds_dwordx4 v[40:41], off
	s_mov_b32 m0, s88
	ds_read_b128 v[100:103], v234 offset:8192
	ds_read_b128 v[96:99], v234 offset:12288
	ds_read_b128 v[164:167], v235 offset:8192
	ds_read_b128 v[160:163], v235 offset:12288
	ds_read_b128 v[140:143], v236 offset:8192
	ds_read_b128 v[136:139], v236 offset:12288
	ds_read_b128 v[132:135], v237 offset:8192
	ds_read_b128 v[128:131], v237 offset:12288
	v_exp_f32_e32 v80, v16
	v_exp_f32_e32 v81, v17
	v_exp_f32_e32 v82, v18
	v_exp_f32_e32 v83, v19
	v_exp_f32_e32 v84, v20
	v_exp_f32_e32 v85, v21
	v_exp_f32_e32 v86, v22
	v_exp_f32_e32 v87, v23
	v_exp_f32_e32 v88, v24
	v_exp_f32_e32 v89, v25
	v_exp_f32_e32 v90, v26
	v_exp_f32_e32 v91, v27
	v_exp_f32_e32 v92, v28
	v_exp_f32_e32 v93, v29
	v_exp_f32_e32 v94, v30
	v_exp_f32_e32 v95, v31
	v_exp_f32_e32 v64, v0
	v_exp_f32_e32 v65, v1
	v_exp_f32_e32 v66, v2
	v_exp_f32_e32 v67, v3
	v_exp_f32_e32 v68, v4
	v_exp_f32_e32 v69, v5
	v_exp_f32_e32 v70, v6
	v_exp_f32_e32 v71, v7
	v_exp_f32_e32 v72, v8
	v_exp_f32_e32 v73, v9
	v_exp_f32_e32 v74, v10
	v_exp_f32_e32 v75, v11
	v_exp_f32_e32 v76, v12
	v_exp_f32_e32 v77, v13
	v_exp_f32_e32 v78, v14
	v_exp_f32_e32 v79, v15
	ds_read_b128 v[218:221], v188
	ds_read_b128 v[222:225], v188 offset:1024
	ds_read_b128 v[226:229], v188 offset:2048
	ds_read_b128 v[230:233], v188 offset:3072
	s_waitcnt vmcnt(3) lgkmcnt(0)
	s_barrier
	v_mov_b32_e32 v33, v193
	v_mov_b32_e32 v34, v193
	v_mov_b32_e32 v35, v193
	v_mov_b32_e32 v36, v193
	v_mov_b32_e32 v37, v193
	v_mov_b32_e32 v38, v193
	v_mov_b32_e32 v39, v193
	v_mov_b32_e32 v40, v193
	v_mov_b32_e32 v41, v193
	v_mov_b32_e32 v42, v193
	v_mov_b32_e32 v43, v193
	v_mov_b32_e32 v44, v193
	v_mov_b32_e32 v45, v193
	v_mov_b32_e32 v16, 0
	v_mov_b32_e32 v17, v193
	v_mov_b32_e32 v18, v193
	v_mov_b32_e32 v19, v193
	v_mov_b32_e32 v20, v193
	v_mov_b32_e32 v21, v193
	v_mov_b32_e32 v22, v193
	v_mov_b32_e32 v23, v193
	v_mov_b32_e32 v24, v193
	v_mov_b32_e32 v25, v193
	v_mov_b32_e32 v26, v193
	v_mov_b32_e32 v27, v193
	v_mov_b32_e32 v28, v193
	v_mov_b32_e32 v29, v193
	v_mov_b32_e32 v30, v193
	v_mov_b32_e32 v31, v193
	v_mov_b32_e32 v0, 0
	v_mov_b32_e32 v1, v193
	v_mov_b32_e32 v2, v193
	v_mov_b32_e32 v3, v193
	v_mov_b32_e32 v4, v193
	v_mov_b32_e32 v5, v193
	v_mov_b32_e32 v6, v193
	v_mov_b32_e32 v7, v193
	v_mov_b32_e32 v8, v193
	v_mov_b32_e32 v9, v193
	v_mov_b32_e32 v10, v193
	v_mov_b32_e32 v11, v193
	v_mov_b32_e32 v12, v193
	v_mov_b32_e32 v13, v193
	v_mov_b32_e32 v14, v193
	v_mov_b32_e32 v15, v193
	.p2align	6

; #define WAIT_BAR(N) asm volatile("s_waitcnt vmcnt(" #N ") lgkmcnt(0)\n\ts_barrier":::"memory")
;   #define DMA_K(t,slot) glds16(ksrc+(long)(t)*KVBLK*KVP,(unsigned)__builtin_amdgcn_readfirstlane(kdst+(slot)))
;   #define DMA_V(t,slot) do{ glds16(vsrc+(long)(t)*KVBLK*KVP,(unsigned)__builtin_amdgcn_readfirstlane(vdst+VM*(slot))); if constexpr(VM==2) glds16(vsrc+64+(long)(t)*KVBLK*KVP,(unsigned)__builtin_amdgcn_readfirstlane(vdst+VM*(slot)+8192)); }while(0)
; template<int THRL,int VM,bool NOMAX> __device__ __forceinline__ void attn_unit(const bf16*Qb,const bf16*__restrict__ Kh,const bf16*__restrict__ Vh,bf16*Ob,const int NT,const int sp,float*wscr,char*shm){
;   int tid_=threadIdx.x; asm volatile("":"+v"(tid_));
;   const int tid=tid_,lane=tid&63,r32=lane&31,hi=lane>>5; const int wid=__builtin_amdgcn_readfirstlane(tid>>6);
;   const bf16*Qw=Qb+(long)(wid*QBLK)*QOP;
;   const unsigned lds0=(unsigned)(uintptr_t)shm;
;   constexpr int LDS_WS_=LDS_V+3*VM*SLOTB, LDS_OST_=LDS_WS_+NW*64*4;
;   float*wsf=(float*)(shm+LDS_WS_)+wid*64;
;   const bf16*ksrc=Kh+(long)lane*KVP+wid*8;
;   const bf16*vsrc=Vh+(long)(16*(wid&3)+(lane>>2))*KVP+(wid>>2)*32+(lane&3)*8;
;   const unsigned kdst=lds0+LDS_K+wid*1024, vdst=lds0+LDS_V+wid*1024;
;     ...
;   const int vb0=(int)(lds0+LDS_V)+((lane>>4)&1)*32+(lane&3)*8+(4*hi+((lane&15)>>2))*64;
;   const char*Kbase=shm+LDS_K; bf16x8 kf[8];
;   const lds_cptr shm3=(lds_cptr)shm; const lds_cptr kp0=shm3+LDS_K+hi*1024+r32*16; const lds_cptr vp0=shm3+LDS_V+((lane>>4)&1)*32+(lane&3)*8+(4*hi+((lane&15)>>2))*64;
;   if(wid>=4)__builtin_amdgcn_s_setprio(1);
;   DMA_K(0,0);DMA_V(0,0);DMA_K(1,SLOTB);
;   bf16x8 qr[4];
;   #pragma unroll
;   for(int d0=0;d0<4;++d0)qr[d0]=*reinterpret_cast<const bf16x8*>(&Qw[(long)r32*QOP+d0*16+hi*8]);
;   const lds_cptr qpk=shm3+LDS_OST_+wid*4096+lane*16;
;   if constexpr(VM==2){
;     #pragma unroll
;     for(int d0=0;d0<4;++d0)*(__attribute__((address_space(3))) bf16x8*)(const_cast<__attribute__((address_space(3))) char*>(qpk)+d0*1024)=qr[d0]; }
;   float mhat=0.f,l_reg=0.f;f32x16 o[2*VM];
;   #pragma unroll
;   for(int d_=0;d_<2*VM;++d_)o[d_]=f32x16{};
;  f32x16 negm=f32x16{}; if constexpr(VM==1){asm volatile("":"+v"(negm));}
;   bool resc=false;
;     ...
;   f32x16 pA0,pA1,pB0,pB1;
;   int sl_prev=0,sl_cur=0,sl_next=SLOTB;
;     ...
;   DMA_K(2,2*SLOTB);
;   WAIT_BAR(3);
.LBB0_873:
	s_xor_b64 s[6:7], s[16:17], -1
	s_lshl_b32 s16, s8, 7
	s_add_u32 s35, s83, s16
	s_addc_u32 s88, s84, 0
	s_add_u32 s16, s0, s16
	s_addc_u32 s17, s1, 0
	s_lshl_b32 s86, s85, 5
	v_and_b32_e32 v187, 63, v32
	s_ashr_i32 s87, s86, 31
	s_lshl_b64 s[86:87], s[86:87], 11
	v_mul_u32_u24_e32 v0, 0x500, v187
	s_add_u32 s86, s35, s86
	v_lshlrev_b32_e32 v168, 1, v0
	s_addc_u32 s87, s88, s87
	v_lshl_add_u64 v[0:1], s[16:17], 0, v[168:169]
	s_lshl_b32 s16, s85, 3
	s_ashr_i32 s17, s16, 31
	v_lshl_add_u64 v[54:55], s[16:17], 1, v[0:1]
	v_and_b32_e32 v246, 63, v210
	v_lshrrev_b32_e32 v247, 6, v210
	v_lshrrev_b32_e32 v248, 3, v246
	v_lshl_add_u32 v248, v247, 3, v248
	v_and_b32_e32 v249, 1, v247
	v_lshrrev_b32_e32 v250, 4, v246
	v_lshl_or_b32 v249, v249, 2, v250
	v_and_b32_e32 v250, 7, v246
	v_xor_b32_e32 v250, v250, v249
	v_sub_u32_e32 v248, v248, v246
	v_mul_i32_i24_e32 v248, 0xa00, v248
	v_sub_u32_e32 v250, v250, v247
	v_lshl_add_u32 v248, v250, 4, v248
	v_ashrrev_i32_e32 v249, 31, v248
	v_lshl_add_u64 v[54:55], v[248:249], 0, v[54:55]
	s_mov_b64 s[16:17], 0x200
	v_lshl_add_u64 v[174:175], v[54:55], 0, s[16:17]
	s_lshl_b32 s16, s85, 4
	v_bfe_u32 v0, v32, 2, 4
	v_and_or_b32 v0, s16, 48, v0
	s_ashr_i32 s16, s34, 3
	v_mul_u32_u24_e32 v0, 0x500, v0
	s_andn2_b32 s16, s16, 31
	v_lshlrev_b32_e32 v168, 1, v0
	s_ashr_i32 s17, s16, 31
	v_lshlrev_b32_e32 v2, 3, v32
	s_lshl_b32 s35, s85, 10
	v_lshl_add_u64 v[0:1], s[0:1], 0, v[168:169]
	v_and_b32_e32 v190, 24, v2
	s_cmp_lg_u32 0, -1
	v_lshl_add_u64 v[0:1], s[16:17], 1, v[0:1]
	v_lshlrev_b32_e32 v168, 1, v190
	s_cselect_b32 s16, 0, 0
	v_lshl_add_u64 v[56:57], v[0:1], 0, v[168:169]
	s_add_i32 s17, s35, s16
	s_mov_b32 s88, m0
	s_mov_b32 m0, s17
	s_nop 0
	global_load_lds_dwordx4 v[174:175], off
	s_mov_b32 m0, s88
	v_lshl_add_u64 v[170:171], v[56:57], 0, s[12:13]
	s_add_i32 s16, s17, 0x6000
	s_mov_b32 s88, m0
	s_mov_b32 m0, s16
	s_nop 0
	global_load_lds_dwordx4 v[170:171], off
	s_mov_b32 m0, s88
	v_and_b32_e32 v186, 31, v32
	v_lshl_add_u64 v[172:173], v[56:57], 0, s[14:15]
	s_add_i32 s88, s17, 0x8000
	s_mov_b32 s89, m0
	s_mov_b32 m0, s88
	s_nop 0
	global_load_lds_dwordx4 v[172:173], off
	s_mov_b32 m0, s89
	v_lshl_add_u64 v[0:1], v[54:55], 0, s[36:37]
	v_bfe_u32 v185, v32, 5, 1
	s_add_i32 s88, s17, 0x2000
	s_mov_b32 s89, m0
	s_mov_b32 m0, s88
	s_nop 0
	global_load_lds_dwordx4 v[0:1], off
	s_mov_b32 m0, s89
	v_lshlrev_b32_e32 v0, 11, v186
	v_lshl_or_b32 v4, v185, 4, v0
	global_load_dwordx4 v[0:3], v4, s[86:87] offset:1024
	global_load_dwordx4 v[34:37], v4, s[86:87] offset:1056
	global_load_dwordx4 v[38:41], v4, s[86:87] offset:1088
	global_load_dwordx4 v[42:45], v4, s[86:87] offset:1120
	s_lshl_b32 s85, s85, 12
	s_add_i32 s85, s85, 0
	v_lshlrev_b32_e32 v6, 4, v187
	s_add_i32 s85, s85, 0x12800
	v_add_u32_e32 v168, s85, v6
	v_lshlrev_b32_e32 v4, 10, v185
	v_lshlrev_b32_e32 v5, 4, v186
	v_add3_u32 v189, 0, v4, v5
	v_bfe_u32 v246, v189, 4, 5
	v_bfe_u32 v247, v189, 10, 1
	v_bfe_u32 v248, v189, 5, 1
	v_bfe_u32 v249, v189, 6, 2
	v_xor_b32_e32 v247, v247, v248
	v_lshlrev_b32_e32 v246, 7, v246
	v_lshl_or_b32 v246, v247, 4, v246
	v_lshl_add_u32 v234, v249, 5, v246
	v_xor_b32_e32 v248, 1, v249
	v_lshl_add_u32 v235, v248, 5, v246
	v_xor_b32_e32 v248, 2, v249
	v_lshl_add_u32 v236, v248, 5, v246
	v_xor_b32_e32 v248, 3, v249
	v_lshl_add_u32 v237, v248, 5, v246
	v_lshl_add_u64 v[4:5], v[54:55], 0, s[40:41]
	s_add_i32 s86, s17, 0x4000
	v_lshlrev_b32_e32 v33, 1, v32
	v_lshlrev_b32_e32 v32, 4, v32
	v_and_b32_e32 v191, 32, v33
	v_and_b32_e32 v32, 0xc0, v32
	v_lshl_or_b32 v192, v185, 8, v32
	v_add_u32_e32 v32, 0, v191
	v_add3_u32 v188, v32, v190, v192
	v_lshl_add_u64 v[32:33], v[54:55], 0, s[42:43]
	s_add_i32 s88, s17, 0xa000
	s_add_i32 s90, s17, 0xc000
	v_mov_b32_e32 v193, 0
	s_mov_b32 s89, 0
	s_movk_i32 s87, 0x2000
	v_lshl_add_u64 v[176:177], v[56:57], 0, s[50:51]
	v_lshl_add_u64 v[178:179], v[56:57], 0, s[52:53]
	v_lshl_add_u64 v[180:181], v[54:55], 0, s[54:55]
	v_mov_b32_e32 v54, v193
	v_mov_b32_e32 v55, v193
	v_mov_b32_e32 v58, v193
	v_mov_b32_e32 v59, v193
	v_mov_b32_e32 v60, v193
	v_mov_b32_e32 v61, v193
	v_mov_b32_e32 v62, v193
	v_mov_b32_e32 v63, v193
	s_waitcnt vmcnt(3)
	ds_write_b128 v168, v[0:3]
	s_waitcnt vmcnt(2)
	ds_write_b128 v168, v[34:37] offset:1024
	s_waitcnt vmcnt(1)
	ds_write_b128 v168, v[38:41] offset:2048
	s_waitcnt vmcnt(0)
	ds_write_b128 v168, v[42:45] offset:3072
	s_mov_b32 s85, m0
	s_mov_b32 m0, s86
	s_nop 0
	global_load_lds_dwordx4 v[4:5], off
	s_mov_b32 m0, s85
	s_waitcnt vmcnt(3) lgkmcnt(0)
	s_barrier
; #define WAIT_BAR(N) asm volatile("s_waitcnt vmcnt(" #N ") lgkmcnt(0)\n\ts_barrier":::"memory")
;   #define DMA_K(t,slot) glds16(ksrc+(long)(t)*KVBLK*KVP,(unsigned)__builtin_amdgcn_readfirstlane(kdst+(slot)))
;   #define DMA_V(t,slot) do{ glds16(vsrc+(long)(t)*KVBLK*KVP,(unsigned)__builtin_amdgcn_readfirstlane(vdst+VM*(slot))); if constexpr(VM==2) glds16(vsrc+64+(long)(t)*KVBLK*KVP,(unsigned)__builtin_amdgcn_readfirstlane(vdst+VM*(slot)+8192)); }while(0)
;   #define ROT() do{sl_prev=sl_cur;sl_cur=sl_next;sl_next=(sl_next==(NSLOT-1)*SLOTB)?0:sl_next+SLOTB;}while(0)
; template<int THRL,int VM,bool NOMAX> __device__ __forceinline__ void attn_unit(const bf16*Qb,const bf16*__restrict__ Kh,const bf16*__restrict__ Vh,bf16*Ob,const int NT,const int sp,float*wscr,char*shm){
;     ...
;   float mhat=0.f,l_reg=0.f;f32x16 o[2*VM];
;   #pragma unroll
;   for(int d_=0;d_<2*VM;++d_)o[d_]=f32x16{};
;     ...
;   DMA_K(2,2*SLOTB);
;   WAIT_BAR(3);
;   qkt(pA0,pA1,Kbase,qr,negm,r32,hi);asm volatile("s_nop 15\n\ts_nop 7":"+v"(pA0),"+v"(pA1));
;   START(pA0,pA1);
;   _Pragma("unroll") for(int r=0;r<16;++r)pA1[r]=__builtin_amdgcn_exp2f(pA1[r]);
;   WAIT_BAR(0);
;   DMA_K(3,0);DMA_V(1,SLOTB);
;   ROT();
;   kload8(kf,kp0+sl_cur);
;   if constexpr(VM==2){WAIT_BAR(3);}else{WAIT_BAR(2);}
	ds_read_b128 v[4:7], v234
	ds_read_b128 v[8:11], v234 offset:4096
	s_waitcnt lgkmcnt(1)
	v_mfma_f32_32x32x16_bf16 v[16:31], v[4:7], v[0:3], 0
	ds_read_b128 v[46:49], v235
	ds_read_b128 v[50:53], v235 offset:4096
	s_mov_b32 s85, -1
	s_movk_i32 s86, 0x4000
	s_waitcnt lgkmcnt(2)
	v_mfma_f32_32x32x16_bf16 v[0:15], v[8:11], v[0:3], 0
	s_waitcnt lgkmcnt(1)
	v_mfma_f32_32x32x16_bf16 v[16:31], v[46:49], v[34:37], v[16:31]
	s_waitcnt lgkmcnt(0)
	v_mfma_f32_32x32x16_bf16 v[0:15], v[50:53], v[34:37], v[0:15]
	ds_read_b128 v[34:37], v236
	ds_read_b128 v[46:49], v236 offset:4096
	s_waitcnt lgkmcnt(1)
	v_mfma_f32_32x32x16_bf16 v[16:31], v[34:37], v[38:41], v[16:31]
	ds_read_b128 v[34:37], v237 offset:4096
	ds_read_b128 v[50:53], v237
	s_waitcnt lgkmcnt(2)
	v_mfma_f32_32x32x16_bf16 v[0:15], v[46:49], v[38:41], v[0:15]
	v_lshl_add_u64 v[38:39], v[56:57], 0, s[44:45]
	v_lshl_add_u64 v[40:41], v[56:57], 0, s[48:49]
	v_mov_b32_e32 v48, 0
	v_mov_b32_e32 v49, v193
	v_mov_b32_e32 v56, v193
	v_mov_b32_e32 v57, v193
	v_mov_b32_e32 v46, v193
	s_waitcnt lgkmcnt(0)
	v_mfma_f32_32x32x16_bf16 v[16:31], v[50:53], v[42:45], v[16:31]
	v_mov_b32_e32 v50, v193
	v_mov_b32_e32 v51, v193
	v_mov_b32_e32 v52, v193
	v_mov_b32_e32 v53, v193
	v_mov_b32_e32 v47, v193
	v_mfma_f32_32x32x16_bf16 v[0:15], v[34:37], v[42:45], v[0:15]
	s_nop 15
	s_nop 7
	s_waitcnt vmcnt(0) lgkmcnt(0)
	s_barrier
	s_mov_b32 s91, m0
	s_mov_b32 m0, s17
	s_nop 0
	global_load_lds_dwordx4 v[32:33], off
	s_mov_b32 m0, s91
	v_mov_b32_e32 v32, 0
	s_mov_b32 s91, m0
	s_mov_b32 m0, s88
	s_nop 0
	global_load_lds_dwordx4 v[38:39], off
	s_mov_b32 m0, s91
	s_mov_b32 s88, m0
	s_mov_b32 m0, s90
	s_nop 0
	global_load_lds_dwordx4 v[40:41], off
	s_mov_b32 m0, s88
	ds_read_b128 v[100:103], v234 offset:8192
	ds_read_b128 v[96:99], v234 offset:12288
	ds_read_b128 v[164:167], v235 offset:8192
	ds_read_b128 v[160:163], v235 offset:12288
	ds_read_b128 v[140:143], v236 offset:8192
	ds_read_b128 v[136:139], v236 offset:12288
	ds_read_b128 v[132:135], v237 offset:8192
	ds_read_b128 v[128:131], v237 offset:12288
	v_exp_f32_e32 v80, v16
	v_exp_f32_e32 v81, v17
	v_exp_f32_e32 v82, v18
	v_exp_f32_e32 v83, v19
	v_exp_f32_e32 v84, v20
	v_exp_f32_e32 v85, v21
	v_exp_f32_e32 v86, v22
	v_exp_f32_e32 v87, v23
	v_exp_f32_e32 v88, v24
	v_exp_f32_e32 v89, v25
	v_exp_f32_e32 v90, v26
	v_exp_f32_e32 v91, v27
	v_exp_f32_e32 v92, v28
	v_exp_f32_e32 v93, v29
	v_exp_f32_e32 v94, v30
	v_exp_f32_e32 v95, v31
	v_exp_f32_e32 v64, v0
	v_exp_f32_e32 v65, v1
	v_exp_f32_e32 v66, v2
	v_exp_f32_e32 v67, v3
	v_exp_f32_e32 v68, v4
	v_exp_f32_e32 v69, v5
	v_exp_f32_e32 v70, v6
	v_exp_f32_e32 v71, v7
	v_exp_f32_e32 v72, v8
	v_exp_f32_e32 v73, v9
	v_exp_f32_e32 v74, v10
	v_exp_f32_e32 v75, v11
	v_exp_f32_e32 v76, v12
	v_exp_f32_e32 v77, v13
	v_exp_f32_e32 v78, v14
	v_exp_f32_e32 v79, v15
	ds_read_b128 v[218:221], v168
	ds_read_b128 v[222:225], v168 offset:1024
	ds_read_b128 v[226:229], v168 offset:2048
	ds_read_b128 v[230:233], v168 offset:3072
	s_waitcnt vmcnt(3) lgkmcnt(0)
	s_barrier
	v_mov_b32_e32 v33, v193
	v_mov_b32_e32 v34, v193
	v_mov_b32_e32 v35, v193
	v_mov_b32_e32 v36, v193
	v_mov_b32_e32 v37, v193
	v_mov_b32_e32 v38, v193
	v_mov_b32_e32 v39, v193
	v_mov_b32_e32 v40, v193
	v_mov_b32_e32 v41, v193
	v_mov_b32_e32 v42, v193
	v_mov_b32_e32 v43, v193
	v_mov_b32_e32 v44, v193
	v_mov_b32_e32 v45, v193
	v_mov_b32_e32 v16, 0
	v_mov_b32_e32 v17, v193
	v_mov_b32_e32 v18, v193
	v_mov_b32_e32 v19, v193
	v_mov_b32_e32 v20, v193
	v_mov_b32_e32 v21, v193
	v_mov_b32_e32 v22, v193
	v_mov_b32_e32 v23, v193
	v_mov_b32_e32 v24, v193
	v_mov_b32_e32 v25, v193
	v_mov_b32_e32 v26, v193
	v_mov_b32_e32 v27, v193
	v_mov_b32_e32 v28, v193
	v_mov_b32_e32 v29, v193
	v_mov_b32_e32 v30, v193
	v_mov_b32_e32 v31, v193
	v_mov_b32_e32 v0, 0
	v_mov_b32_e32 v1, v193
	v_mov_b32_e32 v2, v193
	v_mov_b32_e32 v3, v193
	v_mov_b32_e32 v4, v193
	v_mov_b32_e32 v5, v193
	v_mov_b32_e32 v6, v193
	v_mov_b32_e32 v7, v193
	v_mov_b32_e32 v8, v193
	v_mov_b32_e32 v9, v193
	v_mov_b32_e32 v10, v193
	v_mov_b32_e32 v11, v193
	v_mov_b32_e32 v12, v193
	v_mov_b32_e32 v13, v193
	v_mov_b32_e32 v14, v193
	v_mov_b32_e32 v15, v193
	.p2align	6

; #define WAIT_BAR(N) asm volatile("s_waitcnt vmcnt(" #N ") lgkmcnt(0)\n\ts_barrier":::"memory")
;   #define DMA_K(t,slot) glds16(ksrc+(long)(t)*KVBLK*KVP,(unsigned)__builtin_amdgcn_readfirstlane(kdst+(slot)))
;   #define DMA_V(t,slot) do{ glds16(vsrc+(long)(t)*KVBLK*KVP,(unsigned)__builtin_amdgcn_readfirstlane(vdst+VM*(slot))); if constexpr(VM==2) glds16(vsrc+64+(long)(t)*KVBLK*KVP,(unsigned)__builtin_amdgcn_readfirstlane(vdst+VM*(slot)+8192)); }while(0)
; template<int THRL,int VM,bool NOMAX> __device__ __forceinline__ void attn_unit(const bf16*Qb,const bf16*__restrict__ Kh,const bf16*__restrict__ Vh,bf16*Ob,const int NT,const int sp,float*wscr,char*shm){
;   int tid_=threadIdx.x; asm volatile("":"+v"(tid_));
;   const int tid=tid_,lane=tid&63,r32=lane&31,hi=lane>>5; const int wid=__builtin_amdgcn_readfirstlane(tid>>6);
;   const bf16*Qw=Qb+(long)(wid*QBLK)*QOP;
;   const unsigned lds0=(unsigned)(uintptr_t)shm;
;   constexpr int LDS_WS_=LDS_V+3*VM*SLOTB, LDS_OST_=LDS_WS_+NW*64*4;
;   float*wsf=(float*)(shm+LDS_WS_)+wid*64;
;   const bf16*ksrc=Kh+(long)lane*KVP+wid*8;
;   const bf16*vsrc=Vh+(long)(16*(wid&3)+(lane>>2))*KVP+(wid>>2)*32+(lane&3)*8;
;   const unsigned kdst=lds0+LDS_K+wid*1024, vdst=lds0+LDS_V+wid*1024;
;     ...
;   const int vb0=(int)(lds0+LDS_V)+((lane>>4)&1)*32+(lane&3)*8+(4*hi+((lane&15)>>2))*64;
;   const char*Kbase=shm+LDS_K; bf16x8 kf[8];
;   const lds_cptr shm3=(lds_cptr)shm; const lds_cptr kp0=shm3+LDS_K+hi*1024+r32*16; const lds_cptr vp0=shm3+LDS_V+((lane>>4)&1)*32+(lane&3)*8+(4*hi+((lane&15)>>2))*64;
;   if(wid>=4)__builtin_amdgcn_s_setprio(1);
;   DMA_K(0,0);DMA_V(0,0);DMA_K(1,SLOTB);
;   bf16x8 qr[4];
;   #pragma unroll
;   for(int d0=0;d0<4;++d0)qr[d0]=*reinterpret_cast<const bf16x8*>(&Qw[(long)r32*QOP+d0*16+hi*8]);
;   const lds_cptr qpk=shm3+LDS_OST_+wid*4096+lane*16;
;   if constexpr(VM==2){
;     #pragma unroll
;     for(int d0=0;d0<4;++d0)*(__attribute__((address_space(3))) bf16x8*)(const_cast<__attribute__((address_space(3))) char*>(qpk)+d0*1024)=qr[d0]; }
;   float mhat=0.f,l_reg=0.f;f32x16 o[2*VM];
;   #pragma unroll
;   for(int d_=0;d_<2*VM;++d_)o[d_]=f32x16{};
;  f32x16 negm=f32x16{}; if constexpr(VM==1){asm volatile("":"+v"(negm));}
;   bool resc=false;
;     ...
;   f32x16 pA0,pA1,pB0,pB1;
;   int sl_prev=0,sl_cur=0,sl_next=SLOTB;
;     ...
;   DMA_K(2,2*SLOTB);
;   WAIT_BAR(3);
.LBB0_881:
	s_ashr_i32 s16, s19, 8
	s_ashr_i32 s17, s16, 31
	s_lshl_b32 s33, s19, 19
	s_and_b32 s33, s33, 0xf80000
	s_lshl_b64 s[34:35], s[16:17], 24
	s_add_u32 s17, s20, s34
	s_addc_u32 s34, s21, s35
	s_add_u32 s17, s17, s33
	s_addc_u32 s33, s34, 0
	s_lshl_b32 s34, s19, 2
	s_and_b32 s34, s34, 0x380
	s_add_u32 s50, s17, s34
	s_addc_u32 s33, s33, 0
	s_mul_hi_i32 s17, s16, 0x1400000
	s_mul_i32 s16, s16, 0x1400000
	s_add_u32 s16, s30, s16
	s_addc_u32 s17, s31, s17
	s_and_b32 s34, s19, 0x80
	s_add_u32 s16, s16, s34
	s_addc_u32 s17, s17, 0
	s_lshl_b32 s34, s28, 5
	s_ashr_i32 s35, s34, 31
	v_and_b32_e32 v178, 63, v48
	s_lshl_b64 s[34:35], s[34:35], 11
	s_add_u32 s50, s50, s34
	v_mul_u32_u24_e32 v16, 0x500, v178
	s_addc_u32 s51, s33, s35
	v_lshlrev_b32_e32 v168, 1, v16
	s_lshl_b32 s34, s28, 3
	v_lshl_add_u64 v[16:17], s[16:17], 0, v[168:169]
	s_ashr_i32 s35, s34, 31
	v_lshl_add_u64 v[172:173], s[34:35], 1, v[16:17]
	v_and_b32_e32 v246, 63, v210
	v_lshrrev_b32_e32 v247, 6, v210
	v_lshrrev_b32_e32 v248, 3, v246
	v_lshl_add_u32 v248, v247, 3, v248
	v_and_b32_e32 v249, 1, v247
	v_lshrrev_b32_e32 v250, 4, v246
	v_lshl_or_b32 v249, v249, 2, v250
	v_and_b32_e32 v250, 7, v246
	v_xor_b32_e32 v250, v250, v249
	v_sub_u32_e32 v248, v248, v246
	v_mul_i32_i24_e32 v248, 0xa00, v248
	v_sub_u32_e32 v250, v250, v247
	v_lshl_add_u32 v248, v250, 4, v248
	v_ashrrev_i32_e32 v249, 31, v248
	v_lshl_add_u64 v[172:173], v[248:249], 0, v[172:173]
	s_lshl_b32 s33, s28, 4
	v_bfe_u32 v16, v48, 2, 4
	v_and_or_b32 v16, s33, 48, v16
	v_mul_u32_u24_e32 v16, 0x500, v16
	v_lshlrev_b32_e32 v168, 1, v16
	v_lshl_add_u64 v[16:17], s[16:17], 0, v[168:169]
	s_ashr_i32 s16, s29, 3
	s_andn2_b32 s16, s16, 31
	s_ashr_i32 s17, s16, 31
	v_lshl_add_u64 v[16:17], s[16:17], 1, v[16:17]
	v_lshlrev_b32_e32 v179, 3, v48
	s_lshl_b32 s17, s28, 10
	v_and_b32_e32 v184, 24, v179
	s_cmp_lg_u32 0, -1
	v_lshlrev_b32_e32 v168, 1, v184
	s_cselect_b32 s16, 0, 0
	v_lshl_add_u64 v[88:89], v[16:17], 0, v[168:169]
	s_add_i32 s33, s17, s16
	s_mov_b32 s34, m0
	s_mov_b32 m0, s33
	s_nop 0
	global_load_lds_dwordx4 v[172:173], off
	s_mov_b32 m0, s34
	v_and_b32_e32 v180, 31, v48
	v_lshl_add_u64 v[170:171], v[88:89], 0, s[0:1]
	s_add_i32 s16, s33, 0x6000
	s_mov_b32 s34, m0
	s_mov_b32 m0, s16
	s_nop 0
	global_load_lds_dwordx4 v[170:171], off
	s_mov_b32 m0, s34
	v_lshl_add_u64 v[16:17], v[172:173], 0, s[6:7]
	v_bfe_u32 v181, v48, 5, 1
	s_add_i32 s34, s33, 0x2000
	s_mov_b32 s35, m0
	s_mov_b32 m0, s34
	s_nop 0
	global_load_lds_dwordx4 v[16:17], off
	s_mov_b32 m0, s35
	v_lshlrev_b32_e32 v16, 11, v180
	v_lshl_or_b32 v16, v181, 4, v16
	global_load_dwordx4 v[156:159], v16, s[50:51]
	global_load_dwordx4 v[152:155], v16, s[50:51] offset:32
	global_load_dwordx4 v[148:151], v16, s[50:51] offset:64
	global_load_dwordx4 v[144:147], v16, s[50:51] offset:96
	v_mov_b64_e32 v[30:31], v[14:15]
	v_mov_b64_e32 v[28:29], v[12:13]
	v_mov_b64_e32 v[26:27], v[10:11]
	v_mov_b64_e32 v[24:25], v[8:9]
	v_mov_b64_e32 v[22:23], v[6:7]
	v_mov_b64_e32 v[20:21], v[4:5]
	v_mov_b64_e32 v[18:19], v[2:3]
	v_mov_b64_e32 v[16:17], v[0:1]
	v_lshlrev_b32_e32 v32, 10, v181
	v_lshlrev_b32_e32 v33, 4, v180
	v_add3_u32 v183, 0, v32, v33
	v_bfe_u32 v246, v183, 4, 5
	v_bfe_u32 v247, v183, 10, 1
	v_bfe_u32 v248, v183, 5, 1
	v_bfe_u32 v249, v183, 6, 2
	v_xor_b32_e32 v247, v247, v248
	v_lshlrev_b32_e32 v246, 7, v246
	v_lshl_or_b32 v246, v247, 4, v246
	v_lshl_add_u32 v234, v249, 5, v246
	v_xor_b32_e32 v248, 1, v249
	v_lshl_add_u32 v235, v248, 5, v246
	v_xor_b32_e32 v248, 2, v249
	v_lshl_add_u32 v236, v248, 5, v246
	v_xor_b32_e32 v248, 3, v249
	v_lshl_add_u32 v237, v248, 5, v246
	v_lshl_add_u64 v[32:33], v[172:173], 0, s[8:9]
	s_add_i32 s34, s33, 0x4000
	s_mov_b32 s35, m0
	s_mov_b32 m0, s34
	s_nop 0
	global_load_lds_dwordx4 v[32:33], off
	s_mov_b32 m0, s35
	s_waitcnt vmcnt(3) lgkmcnt(0)
	s_barrier
; #define WAIT_BAR(N) asm volatile("s_waitcnt vmcnt(" #N ") lgkmcnt(0)\n\ts_barrier":::"memory")
;   #define DMA_K(t,slot) glds16(ksrc+(long)(t)*KVBLK*KVP,(unsigned)__builtin_amdgcn_readfirstlane(kdst+(slot)))
;   #define DMA_V(t,slot) do{ glds16(vsrc+(long)(t)*KVBLK*KVP,(unsigned)__builtin_amdgcn_readfirstlane(vdst+VM*(slot))); if constexpr(VM==2) glds16(vsrc+64+(long)(t)*KVBLK*KVP,(unsigned)__builtin_amdgcn_readfirstlane(vdst+VM*(slot)+8192)); }while(0)
;   #define ROT() do{sl_prev=sl_cur;sl_cur=sl_next;sl_next=(sl_next==(NSLOT-1)*SLOTB)?0:sl_next+SLOTB;}while(0)
; template<int THRL,int VM,bool NOMAX> __device__ __forceinline__ void attn_unit(const bf16*Qb,const bf16*__restrict__ Kh,const bf16*__restrict__ Vh,bf16*Ob,const int NT,const int sp,float*wscr,char*shm){
;     ...
;   float mhat=0.f,l_reg=0.f;f32x16 o[2*VM];
;   #pragma unroll
;   for(int d_=0;d_<2*VM;++d_)o[d_]=f32x16{};
;     ...
;   qkt(pA0,pA1,Kbase,qr,negm,r32,hi);asm volatile("s_nop 15\n\ts_nop 7":"+v"(pA0),"+v"(pA1));
;   START(pA0,pA1);
;   _Pragma("unroll") for(int r=0;r<16;++r)pA1[r]=__builtin_amdgcn_exp2f(pA1[r]);
;   WAIT_BAR(0);
;   DMA_K(3,0);DMA_V(1,SLOTB);
;   ROT();
;   kload8(kf,kp0+sl_cur);
;   if constexpr(VM==2){WAIT_BAR(3);}else{WAIT_BAR(2);}
	ds_read_b128 v[50:53], v234
	v_lshlrev_b32_e32 v49, 1, v48
	v_lshlrev_b32_e32 v48, 4, v48
	v_and_b32_e32 v185, 32, v49
	v_and_b32_e32 v48, 0xc0, v48
	v_lshl_or_b32 v168, v181, 8, v48
	v_add_u32_e32 v48, 0, v185
	v_add3_u32 v182, v48, v184, v168
	v_lshl_add_u64 v[48:49], v[172:173], 0, s[10:11]
	s_add_i32 s53, s33, 0x8000
	v_mov_b32_e32 v186, 0
	s_mov_b32 s34, -1
	s_mov_b32 s54, 0
	s_movk_i32 s52, 0x2000
	s_movk_i32 s35, 0x4000
	v_lshl_add_u64 v[174:175], v[88:89], 0, s[14:15]
	v_lshl_add_u64 v[176:177], v[172:173], 0, s[36:37]
	s_waitcnt vmcnt(3) lgkmcnt(0)
	v_mfma_f32_32x32x16_bf16 v[32:47], v[50:53], v[156:159], v[16:31]
	ds_read_b128 v[50:53], v234 offset:4096
	s_waitcnt lgkmcnt(0)
	v_mfma_f32_32x32x16_bf16 v[16:31], v[50:53], v[156:159], v[16:31]
	ds_read_b128 v[50:53], v235
	s_waitcnt vmcnt(2) lgkmcnt(0)
	v_mfma_f32_32x32x16_bf16 v[32:47], v[50:53], v[152:155], v[32:47]
	ds_read_b128 v[50:53], v235 offset:4096
	s_waitcnt lgkmcnt(0)
	v_mfma_f32_32x32x16_bf16 v[16:31], v[50:53], v[152:155], v[16:31]
	ds_read_b128 v[50:53], v236
	s_waitcnt vmcnt(1) lgkmcnt(0)
	v_mfma_f32_32x32x16_bf16 v[32:47], v[50:53], v[148:151], v[32:47]
	ds_read_b128 v[50:53], v236 offset:4096
	ds_read_b128 v[54:57], v237 offset:4096
	ds_read_b128 v[58:61], v237
	s_waitcnt lgkmcnt(2)
	v_mfma_f32_32x32x16_bf16 v[16:31], v[50:53], v[148:151], v[16:31]
	s_waitcnt vmcnt(0) lgkmcnt(0)
	v_mfma_f32_32x32x16_bf16 v[32:47], v[58:61], v[144:147], v[32:47]
	v_lshl_add_u64 v[58:59], v[88:89], 0, s[12:13]
	v_mfma_f32_32x32x16_bf16 v[16:31], v[54:57], v[144:147], v[16:31]
	s_nop 15
	s_nop 7
	s_waitcnt vmcnt(0) lgkmcnt(0)
	s_barrier
	s_mov_b32 s55, m0
	s_mov_b32 m0, s33
	s_nop 0
	global_load_lds_dwordx4 v[48:49], off
	s_mov_b32 m0, s55
	s_nop 0
	s_mov_b32 s55, m0
	s_mov_b32 m0, s53
	s_nop 0
	global_load_lds_dwordx4 v[58:59], off
	s_mov_b32 m0, s55
	ds_read_b128 v[84:87], v234 offset:8192
	ds_read_b128 v[80:83], v234 offset:12288
	ds_read_b128 v[164:167], v235 offset:8192
	ds_read_b128 v[160:163], v235 offset:12288
	ds_read_b128 v[124:127], v236 offset:8192
	ds_read_b128 v[120:123], v236 offset:12288
	ds_read_b128 v[116:119], v237 offset:8192
	ds_read_b128 v[112:115], v237 offset:12288
	s_nop 0
	v_exp_f32_e32 v64, v32
	v_exp_f32_e32 v65, v33
	v_exp_f32_e32 v66, v34
	v_exp_f32_e32 v67, v35
	v_exp_f32_e32 v68, v36
	v_exp_f32_e32 v69, v37
	v_exp_f32_e32 v70, v38
	v_exp_f32_e32 v71, v39
	v_exp_f32_e32 v72, v40
	v_exp_f32_e32 v73, v41
	v_exp_f32_e32 v74, v42
	v_exp_f32_e32 v75, v43
	v_exp_f32_e32 v76, v44
	v_exp_f32_e32 v77, v45
	v_exp_f32_e32 v78, v46
	v_exp_f32_e32 v79, v47
	v_exp_f32_e32 v48, v16
	v_exp_f32_e32 v49, v17
	v_exp_f32_e32 v50, v18
	v_exp_f32_e32 v51, v19
	v_exp_f32_e32 v52, v20
	v_exp_f32_e32 v53, v21
	v_exp_f32_e32 v54, v22
	v_exp_f32_e32 v55, v23
	v_exp_f32_e32 v56, v24
	v_exp_f32_e32 v57, v25
	v_exp_f32_e32 v58, v26
	v_exp_f32_e32 v59, v27
	v_exp_f32_e32 v60, v28
	v_exp_f32_e32 v61, v29
	v_exp_f32_e32 v62, v30
	v_exp_f32_e32 v63, v31
	s_waitcnt vmcnt(2) lgkmcnt(0)
	s_barrier
	v_mov_b32_e32 v16, 0
	v_mov_b32_e32 v17, v186
	v_mov_b32_e32 v18, v186
	v_mov_b32_e32 v19, v186
	v_mov_b32_e32 v20, v186
	v_mov_b32_e32 v21, v186
	v_mov_b32_e32 v22, v186
	v_mov_b32_e32 v23, v186
	v_mov_b32_e32 v24, v186
	v_mov_b32_e32 v25, v186
	v_mov_b32_e32 v26, v186
	v_mov_b32_e32 v27, v186
	v_mov_b32_e32 v28, v186
	v_mov_b32_e32 v29, v186
	v_mov_b32_e32 v30, v186
	v_mov_b32_e32 v31, v186
	v_mov_b32_e32 v32, 0
	v_mov_b32_e32 v33, v186
	v_mov_b32_e32 v34, v186
	v_mov_b32_e32 v35, v186
	v_mov_b32_e32 v36, v186
	v_mov_b32_e32 v37, v186
	v_mov_b32_e32 v38, v186
	v_mov_b32_e32 v39, v186
	v_mov_b32_e32 v40, v186
	v_mov_b32_e32 v41, v186
	v_mov_b32_e32 v42, v186
	v_mov_b32_e32 v43, v186
	v_mov_b32_e32 v44, v186
	v_mov_b32_e32 v45, v186
	v_mov_b32_e32 v46, v186
	v_mov_b32_e32 v47, v186
	.p2align	6

; #define WAIT_BAR(N) asm volatile("s_waitcnt vmcnt(" #N ") lgkmcnt(0)\n\ts_barrier":::"memory")
;   #define DMA_K(t,slot) glds16(ksrc+(long)(t)*KVBLK*KVP,(unsigned)__builtin_amdgcn_readfirstlane(kdst+(slot)))
;   #define DMA_V(t,slot) do{ glds16(vsrc+(long)(t)*KVBLK*KVP,(unsigned)__builtin_amdgcn_readfirstlane(vdst+VM*(slot))); if constexpr(VM==2) glds16(vsrc+64+(long)(t)*KVBLK*KVP,(unsigned)__builtin_amdgcn_readfirstlane(vdst+VM*(slot)+8192)); }while(0)
; template<int THRL,int VM,bool NOMAX> __device__ __forceinline__ void attn_unit(const bf16*Qb,const bf16*__restrict__ Kh,const bf16*__restrict__ Vh,bf16*Ob,const int NT,const int sp,float*wscr,char*shm){
;   int tid_=threadIdx.x; asm volatile("":"+v"(tid_));
;   const int tid=tid_,lane=tid&63,r32=lane&31,hi=lane>>5; const int wid=__builtin_amdgcn_readfirstlane(tid>>6);
;   const bf16*Qw=Qb+(long)(wid*QBLK)*QOP;
;   const unsigned lds0=(unsigned)(uintptr_t)shm;
;   constexpr int LDS_WS_=LDS_V+3*VM*SLOTB, LDS_OST_=LDS_WS_+NW*64*4;
;   float*wsf=(float*)(shm+LDS_WS_)+wid*64;
;   const bf16*ksrc=Kh+(long)lane*KVP+wid*8;
;   const bf16*vsrc=Vh+(long)(16*(wid&3)+(lane>>2))*KVP+(wid>>2)*32+(lane&3)*8;
;   const unsigned kdst=lds0+LDS_K+wid*1024, vdst=lds0+LDS_V+wid*1024;
;     ...
;   const int vb0=(int)(lds0+LDS_V)+((lane>>4)&1)*32+(lane&3)*8+(4*hi+((lane&15)>>2))*64;
;   const char*Kbase=shm+LDS_K; bf16x8 kf[8];
;   const lds_cptr shm3=(lds_cptr)shm; const lds_cptr kp0=shm3+LDS_K+hi*1024+r32*16; const lds_cptr vp0=shm3+LDS_V+((lane>>4)&1)*32+(lane&3)*8+(4*hi+((lane&15)>>2))*64;
;   if(wid>=4)__builtin_amdgcn_s_setprio(1);
;   DMA_K(0,0);DMA_V(0,0);DMA_K(1,SLOTB);
;   bf16x8 qr[4];
;   #pragma unroll
;   for(int d0=0;d0<4;++d0)qr[d0]=*reinterpret_cast<const bf16x8*>(&Qw[(long)r32*QOP+d0*16+hi*8]);
;   const lds_cptr qpk=shm3+LDS_OST_+wid*4096+lane*16;
;   if constexpr(VM==2){
;     #pragma unroll
;     for(int d0=0;d0<4;++d0)*(__attribute__((address_space(3))) bf16x8*)(const_cast<__attribute__((address_space(3))) char*>(qpk)+d0*1024)=qr[d0]; }
;   float mhat=0.f,l_reg=0.f;f32x16 o[2*VM];
;   #pragma unroll
;   for(int d_=0;d_<2*VM;++d_)o[d_]=f32x16{};
;  f32x16 negm=f32x16{}; if constexpr(VM==1){asm volatile("":"+v"(negm));}
;   bool resc=false;
;     ...
;   f32x16 pA0,pA1,pB0,pB1;
;   int sl_prev=0,sl_cur=0,sl_next=SLOTB;
;     ...
;   DMA_K(2,2*SLOTB);
;   WAIT_BAR(3);
.LBB0_890:
	s_ashr_i32 s16, s82, 7
	s_ashr_i32 s17, s16, 31
	s_lshl_b64 s[16:17], s[16:17], 12
	s_add_u32 s33, s16, 0x4000
	s_addc_u32 s17, s17, 0
	s_lshl_b32 s16, s82, 8
	s_and_b32 s16, s16, 0xf00
	s_or_b32 s16, s33, s16
	s_lshl_b64 s[28:29], s[16:17], 11
	s_add_u32 s16, s20, s28
	s_addc_u32 s28, s21, s29
	s_lshl_b32 s29, s82, 3
	s_and_b32 s29, s29, 0x380
	s_add_u32 s34, s16, s29
	s_mul_i32 s16, s17, 0xa00
	s_mul_hi_u32 s17, s33, 0xa00
	s_addc_u32 s35, s28, 0
	s_add_i32 s17, s17, s16
	s_mulk_i32 s33, 0xa00
	s_add_u32 s16, s30, s33
	s_addc_u32 s17, s31, s17
	s_and_b32 s28, s82, 64
	s_lshl_b32 s28, s28, 1
	s_add_u32 s16, s16, s28
	s_addc_u32 s17, s17, 0
	s_lshl_b32 s28, s18, 5
	s_ashr_i32 s29, s28, 31
	v_and_b32_e32 v178, 63, v48
	s_lshl_b64 s[28:29], s[28:29], 11
	s_add_u32 s50, s34, s28
	v_mul_u32_u24_e32 v16, 0x500, v178
	s_addc_u32 s51, s35, s29
	v_lshlrev_b32_e32 v168, 1, v16
	s_lshl_b32 s28, s18, 3
	v_lshl_add_u64 v[16:17], s[16:17], 0, v[168:169]
	s_ashr_i32 s29, s28, 31
	v_lshl_add_u64 v[172:173], s[28:29], 1, v[16:17]
	v_and_b32_e32 v246, 63, v210
	v_lshrrev_b32_e32 v247, 6, v210
	v_lshrrev_b32_e32 v248, 3, v246
	v_lshl_add_u32 v248, v247, 3, v248
	v_and_b32_e32 v249, 1, v247
	v_lshrrev_b32_e32 v250, 4, v246
	v_lshl_or_b32 v249, v249, 2, v250
	v_and_b32_e32 v250, 7, v246
	v_xor_b32_e32 v250, v250, v249
	v_sub_u32_e32 v248, v248, v246
	v_mul_i32_i24_e32 v248, 0xa00, v248
	v_sub_u32_e32 v250, v250, v247
	v_lshl_add_u32 v248, v250, 4, v248
	v_ashrrev_i32_e32 v249, 31, v248
	v_lshl_add_u64 v[172:173], v[248:249], 0, v[172:173]
	s_lshl_b32 s28, s18, 4
	v_bfe_u32 v16, v48, 2, 4
	v_and_or_b32 v16, s28, 48, v16
	v_mul_u32_u24_e32 v16, 0x500, v16
	v_lshlrev_b32_e32 v168, 1, v16
	v_lshl_add_u64 v[16:17], s[16:17], 0, v[168:169]
	s_ashr_i32 s16, s19, 3
	s_andn2_b32 s16, s16, 31
	s_ashr_i32 s17, s16, 31
	v_lshlrev_b32_e32 v179, 3, v48
	s_lshl_b32 s28, s18, 10
	v_and_b32_e32 v183, 24, v179
	s_cmp_lg_u32 0, -1
	v_lshl_add_u64 v[16:17], s[16:17], 1, v[16:17]
	v_lshlrev_b32_e32 v168, 1, v183
	s_cselect_b32 s16, 0, 0
	v_lshl_add_u64 v[88:89], v[16:17], 0, v[168:169]
	s_add_i32 s17, s28, s16
	s_mov_b32 s29, m0
	s_mov_b32 m0, s17
	s_nop 0
	global_load_lds_dwordx4 v[172:173], off
	s_mov_b32 m0, s29
	v_and_b32_e32 v180, 31, v48
	v_lshl_add_u64 v[170:171], v[88:89], 0, s[0:1]
	s_add_i32 s16, s17, 0x6000
	s_mov_b32 s29, m0
	s_mov_b32 m0, s16
	s_nop 0
	global_load_lds_dwordx4 v[170:171], off
	s_mov_b32 m0, s29
	v_lshl_add_u64 v[16:17], v[172:173], 0, s[6:7]
	v_bfe_u32 v181, v48, 5, 1
	s_add_i32 s29, s17, 0x2000
	s_mov_b32 s33, m0
	s_mov_b32 m0, s29
	s_nop 0
	global_load_lds_dwordx4 v[16:17], off
	s_mov_b32 m0, s33
	v_lshlrev_b32_e32 v16, 11, v180
	v_lshl_or_b32 v16, v181, 4, v16
	global_load_dwordx4 v[156:159], v16, s[50:51]
	global_load_dwordx4 v[152:155], v16, s[50:51] offset:32
	global_load_dwordx4 v[148:151], v16, s[50:51] offset:64
	global_load_dwordx4 v[144:147], v16, s[50:51] offset:96
	v_mov_b64_e32 v[30:31], v[14:15]
	v_mov_b64_e32 v[28:29], v[12:13]
	v_mov_b64_e32 v[26:27], v[10:11]
	v_mov_b64_e32 v[24:25], v[8:9]
	v_mov_b64_e32 v[22:23], v[6:7]
	v_mov_b64_e32 v[20:21], v[4:5]
	v_mov_b64_e32 v[18:19], v[2:3]
	v_mov_b64_e32 v[16:17], v[0:1]
	v_lshlrev_b32_e32 v32, 10, v181
	v_lshlrev_b32_e32 v33, 4, v180
	v_add3_u32 v182, 0, v32, v33
	v_bfe_u32 v246, v182, 4, 5
	v_bfe_u32 v247, v182, 10, 1
	v_bfe_u32 v248, v182, 5, 1
	v_bfe_u32 v249, v182, 6, 2
	v_xor_b32_e32 v247, v247, v248
	v_lshlrev_b32_e32 v246, 7, v246
	v_lshl_or_b32 v246, v247, 4, v246
	v_lshl_add_u32 v234, v249, 5, v246
	v_xor_b32_e32 v248, 1, v249
	v_lshl_add_u32 v235, v248, 5, v246
	v_xor_b32_e32 v248, 2, v249
	v_lshl_add_u32 v236, v248, 5, v246
	v_xor_b32_e32 v248, 3, v249
	v_lshl_add_u32 v237, v248, 5, v246
	v_lshl_add_u64 v[32:33], v[172:173], 0, s[8:9]
	s_add_i32 s29, s17, 0x4000
	s_mov_b32 s33, m0
	s_mov_b32 m0, s29
	s_nop 0
	global_load_lds_dwordx4 v[32:33], off
	s_mov_b32 m0, s33
	s_waitcnt vmcnt(3) lgkmcnt(0)
	s_barrier
; #define WAIT_BAR(N) asm volatile("s_waitcnt vmcnt(" #N ") lgkmcnt(0)\n\ts_barrier":::"memory")
;   #define DMA_K(t,slot) glds16(ksrc+(long)(t)*KVBLK*KVP,(unsigned)__builtin_amdgcn_readfirstlane(kdst+(slot)))
;   #define DMA_V(t,slot) do{ glds16(vsrc+(long)(t)*KVBLK*KVP,(unsigned)__builtin_amdgcn_readfirstlane(vdst+VM*(slot))); if constexpr(VM==2) glds16(vsrc+64+(long)(t)*KVBLK*KVP,(unsigned)__builtin_amdgcn_readfirstlane(vdst+VM*(slot)+8192)); }while(0)
;   #define ROT() do{sl_prev=sl_cur;sl_cur=sl_next;sl_next=(sl_next==(NSLOT-1)*SLOTB)?0:sl_next+SLOTB;}while(0)
; template<int THRL,int VM,bool NOMAX> __device__ __forceinline__ void attn_unit(const bf16*Qb,const bf16*__restrict__ Kh,const bf16*__restrict__ Vh,bf16*Ob,const int NT,const int sp,float*wscr,char*shm){
;     ...
;   float mhat=0.f,l_reg=0.f;f32x16 o[2*VM];
;   #pragma unroll
;   for(int d_=0;d_<2*VM;++d_)o[d_]=f32x16{};
;     ...
;   qkt(pA0,pA1,Kbase,qr,negm,r32,hi);asm volatile("s_nop 15\n\ts_nop 7":"+v"(pA0),"+v"(pA1));
;   START(pA0,pA1);
;   _Pragma("unroll") for(int r=0;r<16;++r)pA1[r]=__builtin_amdgcn_exp2f(pA1[r]);
;   WAIT_BAR(0);
;   DMA_K(3,0);DMA_V(1,SLOTB);
;   ROT();
;   kload8(kf,kp0+sl_cur);
;   if constexpr(VM==2){WAIT_BAR(3);}else{WAIT_BAR(2);}
	ds_read_b128 v[50:53], v234
	v_lshlrev_b32_e32 v49, 1, v48
	v_lshlrev_b32_e32 v48, 4, v48
	v_and_b32_e32 v184, 32, v49
	v_and_b32_e32 v48, 0xc0, v48
	v_lshl_or_b32 v185, v181, 8, v48
	v_add_u32_e32 v48, 0, v184
	v_add3_u32 v168, v48, v183, v185
	v_lshl_add_u64 v[48:49], v[172:173], 0, s[10:11]
	s_add_i32 s35, s17, 0x8000
	v_mov_b32_e32 v186, 0
	s_mov_b32 s29, -1
	s_mov_b32 s52, 0
	s_movk_i32 s34, 0x2000
	s_movk_i32 s33, 0x4000
	v_lshl_add_u64 v[174:175], v[88:89], 0, s[14:15]
	v_lshl_add_u64 v[176:177], v[172:173], 0, s[36:37]
	s_waitcnt vmcnt(3) lgkmcnt(0)
	v_mfma_f32_32x32x16_bf16 v[32:47], v[50:53], v[156:159], v[16:31]
	ds_read_b128 v[50:53], v234 offset:4096
	s_waitcnt lgkmcnt(0)
	v_mfma_f32_32x32x16_bf16 v[16:31], v[50:53], v[156:159], v[16:31]
	ds_read_b128 v[50:53], v235
	s_waitcnt vmcnt(2) lgkmcnt(0)
	v_mfma_f32_32x32x16_bf16 v[32:47], v[50:53], v[152:155], v[32:47]
	ds_read_b128 v[50:53], v235 offset:4096
	s_waitcnt lgkmcnt(0)
	v_mfma_f32_32x32x16_bf16 v[16:31], v[50:53], v[152:155], v[16:31]
	ds_read_b128 v[50:53], v236
	s_waitcnt vmcnt(1) lgkmcnt(0)
	v_mfma_f32_32x32x16_bf16 v[32:47], v[50:53], v[148:151], v[32:47]
	ds_read_b128 v[50:53], v236 offset:4096
	ds_read_b128 v[54:57], v237 offset:4096
	ds_read_b128 v[58:61], v237
	s_waitcnt lgkmcnt(2)
	v_mfma_f32_32x32x16_bf16 v[16:31], v[50:53], v[148:151], v[16:31]
	s_waitcnt vmcnt(0) lgkmcnt(0)
	v_mfma_f32_32x32x16_bf16 v[32:47], v[58:61], v[144:147], v[32:47]
	v_lshl_add_u64 v[58:59], v[88:89], 0, s[12:13]
	v_mfma_f32_32x32x16_bf16 v[16:31], v[54:57], v[144:147], v[16:31]
	s_nop 15
	s_nop 7
	s_waitcnt vmcnt(0) lgkmcnt(0)
	s_barrier
	s_mov_b32 s53, m0
	s_mov_b32 m0, s17
	s_nop 0
	global_load_lds_dwordx4 v[48:49], off
	s_mov_b32 m0, s53
	s_nop 0
	s_mov_b32 s53, m0
	s_mov_b32 m0, s35
	s_nop 0
	global_load_lds_dwordx4 v[58:59], off
	s_mov_b32 m0, s53
	ds_read_b128 v[84:87], v234 offset:8192
	ds_read_b128 v[80:83], v234 offset:12288
	ds_read_b128 v[164:167], v235 offset:8192
	ds_read_b128 v[160:163], v235 offset:12288
	ds_read_b128 v[124:127], v236 offset:8192
	ds_read_b128 v[120:123], v236 offset:12288
	ds_read_b128 v[116:119], v237 offset:8192
	ds_read_b128 v[112:115], v237 offset:12288
	s_nop 0
	v_exp_f32_e32 v64, v32
	v_exp_f32_e32 v65, v33
	v_exp_f32_e32 v66, v34
	v_exp_f32_e32 v67, v35
	v_exp_f32_e32 v68, v36
	v_exp_f32_e32 v69, v37
	v_exp_f32_e32 v70, v38
	v_exp_f32_e32 v71, v39
	v_exp_f32_e32 v72, v40
	v_exp_f32_e32 v73, v41
	v_exp_f32_e32 v74, v42
	v_exp_f32_e32 v75, v43
	v_exp_f32_e32 v76, v44
	v_exp_f32_e32 v77, v45
	v_exp_f32_e32 v78, v46
	v_exp_f32_e32 v79, v47
	v_exp_f32_e32 v48, v16
	v_exp_f32_e32 v49, v17
	v_exp_f32_e32 v50, v18
	v_exp_f32_e32 v51, v19
	v_exp_f32_e32 v52, v20
	v_exp_f32_e32 v53, v21
	v_exp_f32_e32 v54, v22
	v_exp_f32_e32 v55, v23
	v_exp_f32_e32 v56, v24
	v_exp_f32_e32 v57, v25
	v_exp_f32_e32 v58, v26
	v_exp_f32_e32 v59, v27
	v_exp_f32_e32 v60, v28
	v_exp_f32_e32 v61, v29
	v_exp_f32_e32 v62, v30
	v_exp_f32_e32 v63, v31
	s_waitcnt vmcnt(2) lgkmcnt(0)
	s_barrier
	v_mov_b32_e32 v16, 0
	v_mov_b32_e32 v17, v186
	v_mov_b32_e32 v18, v186
	v_mov_b32_e32 v19, v186
	v_mov_b32_e32 v20, v186
	v_mov_b32_e32 v21, v186
	v_mov_b32_e32 v22, v186
	v_mov_b32_e32 v23, v186
	v_mov_b32_e32 v24, v186
	v_mov_b32_e32 v25, v186
	v_mov_b32_e32 v26, v186
	v_mov_b32_e32 v27, v186
	v_mov_b32_e32 v28, v186
	v_mov_b32_e32 v29, v186
	v_mov_b32_e32 v30, v186
	v_mov_b32_e32 v31, v186
	v_mov_b32_e32 v32, 0
	v_mov_b32_e32 v33, v186
	v_mov_b32_e32 v34, v186
	v_mov_b32_e32 v35, v186
	v_mov_b32_e32 v36, v186
	v_mov_b32_e32 v37, v186
	v_mov_b32_e32 v38, v186
	v_mov_b32_e32 v39, v186
	v_mov_b32_e32 v40, v186
	v_mov_b32_e32 v41, v186
	v_mov_b32_e32 v42, v186
	v_mov_b32_e32 v43, v186
	v_mov_b32_e32 v44, v186
	v_mov_b32_e32 v45, v186
	v_mov_b32_e32 v46, v186
	v_mov_b32_e32 v47, v186
	.p2align	6

; #define PG8_BAR __builtin_amdgcn_s_barrier()
; template <class Epi, bool ALIGN_EPI = true, bool BLOCKDIAG = false>
; __device__ __forceinline__ void gemm_phase(PG8_LAS unsigned char* lds, const Gemm g, const StaticOrder& S, const Epi& E) {
;     ...
;         const bool has_next = S.next(ui + 1, nxt);
;         const char* nA = has_next ? (const char*)g.A + (size_t)nxt.pm * tstepA : cA; const char* nB = has_next ? (const char*)g.Bt + (size_t)nxt.pn * tstepB : cB;
;         if constexpr (BLOCKDIAG) { PG8_KLOOP(0, nt / 2, 0) PG8_KLOOP(nt / 2, nt, 1) } else { PG8_KLOOP(0, nt, 2) }
;         if constexpr (ALIGN_EPI) { if (wr == 0) PG8_BAR; }
;         E(acc, cur, wr, wc, fr, fq);
;         if (!has_next) break;
; #pragma unroll
;         for (int a = 0; a < 2; ++a)
; #pragma unroll
;             for (int b = 0; b < 2; ++b)
; #pragma unroll
;                 for (int m = 0; m < 4; ++m)
; #pragma unroll
;                     for (int n = 0; n < 2; ++n) acc[a][b][m][n] = (f32x4){0.f, 0.f, 0.f, 0.f};
.LBB0_954:
	s_ashr_i32 s49, s48, 31
	s_lshl_b64 s[16:17], s[48:49], 19
	s_add_u32 s50, s72, s16
	s_addc_u32 s51, s73, s17
	s_and_b64 s[16:17], s[0:1], exec
	s_cselect_b32 s16, s51, s55
	s_cselect_b32 s17, s50, s54
	s_ashr_i32 s45, s44, 31
	s_lshl_b64 s[52:53], s[44:45], 19
	s_add_u32 s52, s18, s52
	s_addc_u32 s53, s19, s53
	s_and_b64 s[58:59], s[0:1], exec
	s_cselect_b32 s45, s53, s57
	s_cselect_b32 s49, s52, s56
	s_add_u32 s54, s54, 0x40080
	s_addc_u32 s55, s55, 0
	s_add_u32 s75, s56, 0x100
	v_mov_b32_e32 v0, 0
	s_addc_u32 s76, s57, 0
	s_mov_b32 s77, -2
	v_mov_b32_e32 v1, v0
	v_mov_b32_e32 v2, v0
	v_mov_b32_e32 v3, v0
	v_mov_b32_e32 v4, v0
	v_mov_b32_e32 v5, v0
	v_mov_b32_e32 v6, v0
	v_mov_b32_e32 v7, v0
	v_mov_b32_e32 v16, v0
	v_mov_b32_e32 v17, v0
	v_mov_b32_e32 v18, v0
	v_mov_b32_e32 v19, v0
	v_mov_b32_e32 v20, v0
	v_mov_b32_e32 v21, v0
	v_mov_b32_e32 v22, v0
	v_mov_b32_e32 v23, v0
	v_mov_b32_e32 v32, v0
	v_mov_b32_e32 v33, v0
	v_mov_b32_e32 v34, v0
	v_mov_b32_e32 v35, v0
	v_mov_b32_e32 v36, v0
	v_mov_b32_e32 v37, v0
	v_mov_b32_e32 v38, v0
	v_mov_b32_e32 v39, v0
	v_mov_b32_e32 v48, v0
	v_mov_b32_e32 v49, v0
	v_mov_b32_e32 v50, v0
	v_mov_b32_e32 v51, v0
	v_mov_b32_e32 v52, v0
	v_mov_b32_e32 v53, v0
	v_mov_b32_e32 v54, v0
	v_mov_b32_e32 v55, v0
	v_mov_b32_e32 v8, v0
	v_mov_b32_e32 v9, v0
	v_mov_b32_e32 v10, v0
	v_mov_b32_e32 v11, v0
	v_mov_b32_e32 v12, v0
	v_mov_b32_e32 v13, v0
	v_mov_b32_e32 v14, v0
	v_mov_b32_e32 v15, v0
	v_mov_b32_e32 v24, v0
	v_mov_b32_e32 v25, v0
	v_mov_b32_e32 v26, v0
	v_mov_b32_e32 v27, v0
	v_mov_b32_e32 v28, v0
	v_mov_b32_e32 v29, v0
	v_mov_b32_e32 v30, v0
	v_mov_b32_e32 v31, v0
	v_mov_b32_e32 v40, v0
	v_mov_b32_e32 v41, v0
	v_mov_b32_e32 v42, v0
	v_mov_b32_e32 v43, v0
	v_mov_b32_e32 v44, v0
	v_mov_b32_e32 v45, v0
	v_mov_b32_e32 v46, v0
	v_mov_b32_e32 v47, v0
	v_mov_b32_e32 v56, v0
	v_mov_b32_e32 v57, v0
	v_mov_b32_e32 v58, v0
	v_mov_b32_e32 v59, v0
	v_mov_b32_e32 v60, v0
	v_mov_b32_e32 v61, v0
	v_mov_b32_e32 v62, v0
	v_mov_b32_e32 v63, v0
	v_mov_b32_e32 v64, v0
	v_mov_b32_e32 v65, v0
	v_mov_b32_e32 v66, v0
	v_mov_b32_e32 v67, v0
	v_mov_b32_e32 v68, v0
	v_mov_b32_e32 v69, v0
	v_mov_b32_e32 v70, v0
	v_mov_b32_e32 v71, v0
	v_mov_b32_e32 v80, v0
	v_mov_b32_e32 v81, v0
	v_mov_b32_e32 v82, v0
	v_mov_b32_e32 v83, v0
	v_mov_b32_e32 v84, v0
	v_mov_b32_e32 v85, v0
	v_mov_b32_e32 v86, v0
	v_mov_b32_e32 v87, v0
	v_mov_b32_e32 v96, v0
	v_mov_b32_e32 v97, v0
	v_mov_b32_e32 v98, v0
	v_mov_b32_e32 v99, v0
	v_mov_b32_e32 v100, v0
	v_mov_b32_e32 v101, v0
	v_mov_b32_e32 v102, v0
	v_mov_b32_e32 v103, v0
	v_mov_b32_e32 v112, v0
	v_mov_b32_e32 v113, v0
	v_mov_b32_e32 v114, v0
	v_mov_b32_e32 v115, v0
	v_mov_b32_e32 v116, v0
	v_mov_b32_e32 v117, v0
	v_mov_b32_e32 v118, v0
	v_mov_b32_e32 v119, v0
	v_mov_b32_e32 v72, v0
	v_mov_b32_e32 v73, v0
	v_mov_b32_e32 v74, v0
	v_mov_b32_e32 v75, v0
	v_mov_b32_e32 v76, v0
	v_mov_b32_e32 v77, v0
	v_mov_b32_e32 v78, v0
	v_mov_b32_e32 v79, v0
	v_mov_b32_e32 v88, v0
	v_mov_b32_e32 v89, v0
	v_mov_b32_e32 v90, v0
	v_mov_b32_e32 v91, v0
	v_mov_b32_e32 v92, v0
	v_mov_b32_e32 v93, v0
	v_mov_b32_e32 v94, v0
	v_mov_b32_e32 v95, v0
	v_mov_b32_e32 v104, v0
	v_mov_b32_e32 v105, v0
	v_mov_b32_e32 v106, v0
	v_mov_b32_e32 v107, v0
	v_mov_b32_e32 v108, v0
	v_mov_b32_e32 v109, v0
	v_mov_b32_e32 v110, v0
	v_mov_b32_e32 v111, v0
	v_mov_b32_e32 v120, v0
	v_mov_b32_e32 v121, v0
	v_mov_b32_e32 v122, v0
	v_mov_b32_e32 v123, v0
	v_mov_b32_e32 v124, v0
	v_mov_b32_e32 v125, v0
	v_mov_b32_e32 v126, v0
	v_mov_b32_e32 v127, v0
	.p2align	6

; template <class Epi, bool ALIGN_EPI = true, bool BLOCKDIAG = false>
; __device__ __forceinline__ void gemm_phase(PG8_LAS unsigned char* lds, const Gemm g, const StaticOrder& S, const Epi& E) {
;     ...
;     for (;;) {
;         const bool has_next = S.next(ui + 1, nxt);
;         const char* nA = has_next ? (const char*)g.A + (size_t)nxt.pm * tstepA : cA; const char* nB = has_next ? (const char*)g.Bt + (size_t)nxt.pn * tstepB : cB;
;         if constexpr (BLOCKDIAG) { PG8_KLOOP(0, nt / 2, 0) PG8_KLOOP(nt / 2, nt, 1) } else { PG8_KLOOP(0, nt, 2) }
;     ...
;         cur = nxt; cA = nA; cB = nB; ++ui;
.LBB0_967:
	s_and_b64 vcc, exec, s[6:7]
	s_mov_b32 s34, s64
	s_mov_b32 s72, s66
	s_mov_b64 s[76:77], s[70:71]
	s_mov_b64 s[74:75], s[68:69]
	s_cbranch_vccnz .LBB0_975
	.p2align	6

; #define PG8_BAR __builtin_amdgcn_s_barrier()
; template <class Epi, bool ALIGN_EPI = true, bool BLOCKDIAG = false>
; __device__ __forceinline__ void gemm_phase(PG8_LAS unsigned char* lds, const Gemm g, const StaticOrder& S, const Epi& E) {
;     ...
;         const bool has_next = S.next(ui + 1, nxt);
;         const char* nA = has_next ? (const char*)g.A + (size_t)nxt.pm * tstepA : cA; const char* nB = has_next ? (const char*)g.Bt + (size_t)nxt.pn * tstepB : cB;
;         if constexpr (BLOCKDIAG) { PG8_KLOOP(0, nt / 2, 0) PG8_KLOOP(nt / 2, nt, 1) } else { PG8_KLOOP(0, nt, 2) }
;         if constexpr (ALIGN_EPI) { if (wr == 0) PG8_BAR; }
;         E(acc, cur, wr, wc, fr, fq);
;         if (!has_next) break;
; #pragma unroll
;         for (int a = 0; a < 2; ++a)
; #pragma unroll
;             for (int b = 0; b < 2; ++b)
; #pragma unroll
;                 for (int m = 0; m < 4; ++m)
; #pragma unroll
;                     for (int n = 0; n < 2; ++n) acc[a][b][m][n] = (f32x4){0.f, 0.f, 0.f, 0.f};
.LBB0_1038:
	s_ashr_i32 s41, s40, 31
	s_lshl_b64 s[16:17], s[40:41], 20
	s_add_u32 s42, s30, s16
	s_addc_u32 s43, s31, s17
	s_and_b64 s[16:17], s[8:9], exec
	s_cselect_b32 s16, s43, s55
	s_cselect_b32 s17, s42, s54
	s_ashr_i32 s39, s38, 31
	s_lshl_b64 s[34:35], s[38:39], 19
	s_add_u32 s44, s18, s34
	s_addc_u32 s45, s19, s35
	s_and_b64 s[34:35], s[8:9], exec
	s_cselect_b32 s34, s45, s53
	s_cselect_b32 s35, s44, s52
	s_add_u32 s39, s52, 0x100
	s_addc_u32 s41, s53, 0
	s_add_u32 s52, s54, 0x80080
	v_mov_b32_e32 v0, 0
	s_addc_u32 s53, s55, 0
	s_mov_b32 s49, -2
	s_waitcnt lgkmcnt(0)
	v_mov_b32_e32 v1, v0
	v_mov_b32_e32 v2, v0
	v_mov_b32_e32 v3, v0
	v_mov_b32_e32 v4, v0
	v_mov_b32_e32 v5, v0
	v_mov_b32_e32 v6, v0
	v_mov_b32_e32 v7, v0
	v_mov_b32_e32 v16, v0
	v_mov_b32_e32 v17, v0
	v_mov_b32_e32 v18, v0
	v_mov_b32_e32 v19, v0
	v_mov_b32_e32 v20, v0
	v_mov_b32_e32 v21, v0
	v_mov_b32_e32 v22, v0
	v_mov_b32_e32 v23, v0
	v_mov_b32_e32 v32, v0
	v_mov_b32_e32 v33, v0
	v_mov_b32_e32 v34, v0
	v_mov_b32_e32 v35, v0
	v_mov_b32_e32 v36, v0
	v_mov_b32_e32 v37, v0
	v_mov_b32_e32 v38, v0
	v_mov_b32_e32 v39, v0
	v_mov_b32_e32 v48, v0
	v_mov_b32_e32 v49, v0
	v_mov_b32_e32 v50, v0
	v_mov_b32_e32 v51, v0
	v_mov_b32_e32 v52, v0
	v_mov_b32_e32 v53, v0
	v_mov_b32_e32 v54, v0
	v_mov_b32_e32 v55, v0
	v_mov_b32_e32 v8, v0
	v_mov_b32_e32 v9, v0
	v_mov_b32_e32 v10, v0
	v_mov_b32_e32 v11, v0
	v_mov_b32_e32 v12, v0
	v_mov_b32_e32 v13, v0
	v_mov_b32_e32 v14, v0
	v_mov_b32_e32 v15, v0
	v_mov_b32_e32 v24, v0
	v_mov_b32_e32 v25, v0
	v_mov_b32_e32 v26, v0
	v_mov_b32_e32 v27, v0
	v_mov_b32_e32 v28, v0
	v_mov_b32_e32 v29, v0
	v_mov_b32_e32 v30, v0
	v_mov_b32_e32 v31, v0
	v_mov_b32_e32 v40, v0
	v_mov_b32_e32 v41, v0
	v_mov_b32_e32 v42, v0
	v_mov_b32_e32 v43, v0
	v_mov_b32_e32 v44, v0
	v_mov_b32_e32 v45, v0
	v_mov_b32_e32 v46, v0
	v_mov_b32_e32 v47, v0
	v_mov_b32_e32 v64, v0
	v_mov_b32_e32 v65, v0
	v_mov_b32_e32 v66, v0
	v_mov_b32_e32 v67, v0
	v_mov_b32_e32 v72, v0
	v_mov_b32_e32 v73, v0
	v_mov_b32_e32 v74, v0
	v_mov_b32_e32 v75, v0
	v_mov_b32_e32 v80, v0
	v_mov_b32_e32 v81, v0
	v_mov_b32_e32 v82, v0
	v_mov_b32_e32 v83, v0
	v_mov_b32_e32 v84, v0
	v_mov_b32_e32 v85, v0
	v_mov_b32_e32 v86, v0
	v_mov_b32_e32 v87, v0
	v_mov_b32_e32 v96, v0
	v_mov_b32_e32 v97, v0
	v_mov_b32_e32 v98, v0
	v_mov_b32_e32 v99, v0
	v_mov_b32_e32 v100, v0
	v_mov_b32_e32 v101, v0
	v_mov_b32_e32 v102, v0
	v_mov_b32_e32 v103, v0
	v_mov_b32_e32 v112, v0
	v_mov_b32_e32 v113, v0
	v_mov_b32_e32 v114, v0
	v_mov_b32_e32 v115, v0
	v_mov_b32_e32 v116, v0
	v_mov_b32_e32 v117, v0
	v_mov_b32_e32 v118, v0
	v_mov_b32_e32 v119, v0
	v_mov_b32_e32 v128, v0
	v_mov_b32_e32 v129, v0
	v_mov_b32_e32 v130, v0
	v_mov_b32_e32 v131, v0
	v_mov_b32_e32 v132, v0
	v_mov_b32_e32 v133, v0
	v_mov_b32_e32 v134, v0
	v_mov_b32_e32 v135, v0
	v_mov_b32_e32 v88, v0
	v_mov_b32_e32 v89, v0
	v_mov_b32_e32 v90, v0
	v_mov_b32_e32 v91, v0
	v_mov_b32_e32 v92, v0
	v_mov_b32_e32 v93, v0
	v_mov_b32_e32 v94, v0
	v_mov_b32_e32 v95, v0
	v_mov_b32_e32 v104, v0
	v_mov_b32_e32 v105, v0
	v_mov_b32_e32 v106, v0
	v_mov_b32_e32 v107, v0
	v_mov_b32_e32 v108, v0
	v_mov_b32_e32 v109, v0
	v_mov_b32_e32 v110, v0
	v_mov_b32_e32 v111, v0
	v_mov_b32_e32 v120, v0
	v_mov_b32_e32 v121, v0
	v_mov_b32_e32 v122, v0
	v_mov_b32_e32 v123, v0
	v_mov_b32_e32 v124, v0
	v_mov_b32_e32 v125, v0
	v_mov_b32_e32 v126, v0
	v_mov_b32_e32 v127, v0
	v_mov_b32_e32 v136, v0
	v_mov_b32_e32 v137, v0
	v_mov_b32_e32 v138, v0
	v_mov_b32_e32 v139, v0
	v_mov_b32_e32 v140, v0
	v_mov_b32_e32 v141, v0
	v_mov_b32_e32 v142, v0
	v_mov_b32_e32 v143, v0
	.p2align	6

; #define PG8_BAR __builtin_amdgcn_s_barrier()
; template <class Epi, bool ALIGN_EPI = true, bool BLOCKDIAG = false>
; __device__ __forceinline__ void gemm_phase(PG8_LAS unsigned char* lds, const Gemm g, const StaticOrder& S, const Epi& E) {
;     ...
;         const bool has_next = S.next(ui + 1, nxt);
;         const char* nA = has_next ? (const char*)g.A + (size_t)nxt.pm * tstepA : cA; const char* nB = has_next ? (const char*)g.Bt + (size_t)nxt.pn * tstepB : cB;
;         if constexpr (BLOCKDIAG) { PG8_KLOOP(0, nt / 2, 0) PG8_KLOOP(nt / 2, nt, 1) } else { PG8_KLOOP(0, nt, 2) }
;         if constexpr (ALIGN_EPI) { if (wr == 0) PG8_BAR; }
;         E(acc, cur, wr, wc, fr, fq);
;         if (!has_next) break;
; #pragma unroll
;         for (int a = 0; a < 2; ++a)
; #pragma unroll
;             for (int b = 0; b < 2; ++b)
; #pragma unroll
;                 for (int m = 0; m < 4; ++m)
; #pragma unroll
;                     for (int n = 0; n < 2; ++n) acc[a][b][m][n] = (f32x4){0.f, 0.f, 0.f, 0.f};
.LBB0_1156:
	s_ashr_i32 s39, s38, 31
	s_lshl_b64 s[16:17], s[38:39], 19
	s_add_u32 s40, s20, s16
	s_addc_u32 s41, s21, s17
	s_and_b64 s[16:17], s[6:7], exec
	s_cselect_b32 s9, s41, s1
	s_cselect_b32 s16, s40, s0
	s_ashr_i32 s37, s36, 31
	s_lshl_b64 s[42:43], s[36:37], 19
	s_add_u32 s42, s18, s42
	s_addc_u32 s43, s19, s43
	s_and_b64 s[48:49], s[6:7], exec
	s_cselect_b32 s17, s43, s47
	s_cselect_b32 s37, s42, s46
	s_add_u32 s0, s0, 0x40080
	s_addc_u32 s1, s1, 0
	s_add_u32 s39, s46, 0x100
	v_mov_b32_e32 v0, 0
	s_addc_u32 s61, s47, 0
	s_mov_b32 s62, -2
	v_mov_b32_e32 v1, v0
	v_mov_b32_e32 v2, v0
	v_mov_b32_e32 v3, v0
	v_mov_b32_e32 v8, v0
	v_mov_b32_e32 v9, v0
	v_mov_b32_e32 v10, v0
	v_mov_b32_e32 v11, v0
	v_mov_b32_e32 v16, v0
	v_mov_b32_e32 v17, v0
	v_mov_b32_e32 v18, v0
	v_mov_b32_e32 v19, v0
	v_mov_b32_e32 v24, v0
	v_mov_b32_e32 v25, v0
	v_mov_b32_e32 v26, v0
	v_mov_b32_e32 v27, v0
	v_mov_b32_e32 v32, v0
	v_mov_b32_e32 v33, v0
	v_mov_b32_e32 v34, v0
	v_mov_b32_e32 v35, v0
	v_mov_b32_e32 v40, v0
	v_mov_b32_e32 v41, v0
	v_mov_b32_e32 v42, v0
	v_mov_b32_e32 v43, v0
	v_mov_b32_e32 v48, v0
	v_mov_b32_e32 v49, v0
	v_mov_b32_e32 v50, v0
	v_mov_b32_e32 v51, v0
	v_mov_b32_e32 v56, v0
	v_mov_b32_e32 v57, v0
	v_mov_b32_e32 v58, v0
	v_mov_b32_e32 v59, v0
	v_mov_b32_e32 v4, v0
	v_mov_b32_e32 v5, v0
	v_mov_b32_e32 v6, v0
	v_mov_b32_e32 v7, v0
	v_mov_b32_e32 v12, v0
	v_mov_b32_e32 v13, v0
	v_mov_b32_e32 v14, v0
	v_mov_b32_e32 v15, v0
	v_mov_b32_e32 v20, v0
	v_mov_b32_e32 v21, v0
	v_mov_b32_e32 v22, v0
	v_mov_b32_e32 v23, v0
	v_mov_b32_e32 v28, v0
	v_mov_b32_e32 v29, v0
	v_mov_b32_e32 v30, v0
	v_mov_b32_e32 v31, v0
	v_mov_b32_e32 v36, v0
	v_mov_b32_e32 v37, v0
	v_mov_b32_e32 v38, v0
	v_mov_b32_e32 v39, v0
	v_mov_b32_e32 v44, v0
	v_mov_b32_e32 v45, v0
	v_mov_b32_e32 v46, v0
	v_mov_b32_e32 v47, v0
	v_mov_b32_e32 v52, v0
	v_mov_b32_e32 v53, v0
	v_mov_b32_e32 v54, v0
	v_mov_b32_e32 v55, v0
	v_mov_b32_e32 v60, v0
	v_mov_b32_e32 v61, v0
	v_mov_b32_e32 v62, v0
	v_mov_b32_e32 v63, v0
	v_mov_b32_e32 v64, v0
	v_mov_b32_e32 v65, v0
	v_mov_b32_e32 v66, v0
	v_mov_b32_e32 v67, v0
	v_mov_b32_e32 v72, v0
	v_mov_b32_e32 v73, v0
	v_mov_b32_e32 v74, v0
	v_mov_b32_e32 v75, v0
	v_mov_b32_e32 v80, v0
	v_mov_b32_e32 v81, v0
	v_mov_b32_e32 v82, v0
	v_mov_b32_e32 v83, v0
	v_mov_b32_e32 v88, v0
	v_mov_b32_e32 v89, v0
	v_mov_b32_e32 v90, v0
	v_mov_b32_e32 v91, v0
	v_mov_b32_e32 v96, v0
	v_mov_b32_e32 v97, v0
	v_mov_b32_e32 v98, v0
	v_mov_b32_e32 v99, v0
	v_mov_b32_e32 v104, v0
	v_mov_b32_e32 v105, v0
	v_mov_b32_e32 v106, v0
	v_mov_b32_e32 v107, v0
	v_mov_b32_e32 v112, v0
	v_mov_b32_e32 v113, v0
	v_mov_b32_e32 v114, v0
	v_mov_b32_e32 v115, v0
	v_mov_b32_e32 v120, v0
	v_mov_b32_e32 v121, v0
	v_mov_b32_e32 v122, v0
	v_mov_b32_e32 v123, v0
	v_mov_b32_e32 v68, v0
	v_mov_b32_e32 v69, v0
	v_mov_b32_e32 v70, v0
	v_mov_b32_e32 v71, v0
	v_mov_b32_e32 v76, v0
	v_mov_b32_e32 v77, v0
	v_mov_b32_e32 v78, v0
	v_mov_b32_e32 v79, v0
	v_mov_b32_e32 v84, v0
	v_mov_b32_e32 v85, v0
	v_mov_b32_e32 v86, v0
	v_mov_b32_e32 v87, v0
	v_mov_b32_e32 v92, v0
	v_mov_b32_e32 v93, v0
	v_mov_b32_e32 v94, v0
	v_mov_b32_e32 v95, v0
	v_mov_b32_e32 v100, v0
	v_mov_b32_e32 v101, v0
	v_mov_b32_e32 v102, v0
	v_mov_b32_e32 v103, v0
	v_mov_b32_e32 v108, v0
	v_mov_b32_e32 v109, v0
	v_mov_b32_e32 v110, v0
	v_mov_b32_e32 v111, v0
	v_mov_b32_e32 v116, v0
	v_mov_b32_e32 v117, v0
	v_mov_b32_e32 v118, v0
	v_mov_b32_e32 v119, v0
	v_mov_b32_e32 v124, v0
	v_mov_b32_e32 v125, v0
	v_mov_b32_e32 v126, v0
	v_mov_b32_e32 v127, v0
	.p2align	6

; template <class Epi, bool ALIGN_EPI = true, bool BLOCKDIAG = false>
; __device__ __forceinline__ void gemm_phase(PG8_LAS unsigned char* lds, const Gemm g, const StaticOrder& S, const Epi& E) {
;     ...
; #pragma unroll
;         for (int a = 0; a < 2; ++a)
; #pragma unroll
;             for (int b = 0; b < 2; ++b)
; #pragma unroll
;                 for (int m = 0; m < 4; ++m)
; #pragma unroll
;                     for (int n = 0; n < 2; ++n) acc[a][b][m][n] = (f32x4){0.f, 0.f, 0.f, 0.f};
.LBB0_1247:
	s_add_u32 s53, s18, 0x100
	v_mov_b32_e32 v0, 0
	s_addc_u32 s54, s19, 0
	s_mov_b32 s55, -2
	v_mov_b32_e32 v1, v0
	v_mov_b32_e32 v2, v0
	v_mov_b32_e32 v3, v0
	v_mov_b32_e32 v4, v0
	v_mov_b32_e32 v5, v0
	v_mov_b32_e32 v6, v0
	v_mov_b32_e32 v7, v0
	v_mov_b32_e32 v16, v0
	v_mov_b32_e32 v17, v0
	v_mov_b32_e32 v18, v0
	v_mov_b32_e32 v19, v0
	v_mov_b32_e32 v20, v0
	v_mov_b32_e32 v21, v0
	v_mov_b32_e32 v22, v0
	v_mov_b32_e32 v23, v0
	v_mov_b32_e32 v32, v0
	v_mov_b32_e32 v33, v0
	v_mov_b32_e32 v34, v0
	v_mov_b32_e32 v35, v0
	v_mov_b32_e32 v36, v0
	v_mov_b32_e32 v37, v0
	v_mov_b32_e32 v38, v0
	v_mov_b32_e32 v39, v0
	v_mov_b32_e32 v48, v0
	v_mov_b32_e32 v49, v0
	v_mov_b32_e32 v50, v0
	v_mov_b32_e32 v51, v0
	v_mov_b32_e32 v52, v0
	v_mov_b32_e32 v53, v0
	v_mov_b32_e32 v54, v0
	v_mov_b32_e32 v55, v0
	v_mov_b32_e32 v8, v0
	v_mov_b32_e32 v9, v0
	v_mov_b32_e32 v10, v0
	v_mov_b32_e32 v11, v0
	v_mov_b32_e32 v12, v0
	v_mov_b32_e32 v13, v0
	v_mov_b32_e32 v14, v0
	v_mov_b32_e32 v15, v0
	v_mov_b32_e32 v24, v0
	v_mov_b32_e32 v25, v0
	v_mov_b32_e32 v26, v0
	v_mov_b32_e32 v27, v0
	v_mov_b32_e32 v28, v0
	v_mov_b32_e32 v29, v0
	v_mov_b32_e32 v30, v0
	v_mov_b32_e32 v31, v0
	v_mov_b32_e32 v40, v0
	v_mov_b32_e32 v41, v0
	v_mov_b32_e32 v42, v0
	v_mov_b32_e32 v43, v0
	v_mov_b32_e32 v44, v0
	v_mov_b32_e32 v45, v0
	v_mov_b32_e32 v46, v0
	v_mov_b32_e32 v47, v0
	v_mov_b32_e32 v56, v0
	v_mov_b32_e32 v57, v0
	v_mov_b32_e32 v58, v0
	v_mov_b32_e32 v59, v0
	v_mov_b32_e32 v60, v0
	v_mov_b32_e32 v61, v0
	v_mov_b32_e32 v62, v0
	v_mov_b32_e32 v63, v0
	v_mov_b32_e32 v64, v0
	v_mov_b32_e32 v65, v0
	v_mov_b32_e32 v66, v0
	v_mov_b32_e32 v67, v0
	v_mov_b32_e32 v68, v0
	v_mov_b32_e32 v69, v0
	v_mov_b32_e32 v70, v0
	v_mov_b32_e32 v71, v0
	v_mov_b32_e32 v80, v0
	v_mov_b32_e32 v81, v0
	v_mov_b32_e32 v82, v0
	v_mov_b32_e32 v83, v0
	v_mov_b32_e32 v84, v0
	v_mov_b32_e32 v85, v0
	v_mov_b32_e32 v86, v0
	v_mov_b32_e32 v87, v0
	v_mov_b32_e32 v96, v0
	v_mov_b32_e32 v97, v0
	v_mov_b32_e32 v98, v0
	v_mov_b32_e32 v99, v0
	v_mov_b32_e32 v100, v0
	v_mov_b32_e32 v101, v0
	v_mov_b32_e32 v102, v0
	v_mov_b32_e32 v103, v0
	v_mov_b32_e32 v112, v0
	v_mov_b32_e32 v113, v0
	v_mov_b32_e32 v114, v0
	v_mov_b32_e32 v115, v0
	v_mov_b32_e32 v116, v0
	v_mov_b32_e32 v117, v0
	v_mov_b32_e32 v118, v0
	v_mov_b32_e32 v119, v0
	v_mov_b32_e32 v72, v0
	v_mov_b32_e32 v73, v0
	v_mov_b32_e32 v74, v0
	v_mov_b32_e32 v75, v0
	v_mov_b32_e32 v76, v0
	v_mov_b32_e32 v77, v0
	v_mov_b32_e32 v78, v0
	v_mov_b32_e32 v79, v0
	v_mov_b32_e32 v88, v0
	v_mov_b32_e32 v89, v0
	v_mov_b32_e32 v90, v0
	v_mov_b32_e32 v91, v0
	v_mov_b32_e32 v92, v0
	v_mov_b32_e32 v93, v0
	v_mov_b32_e32 v94, v0
	v_mov_b32_e32 v95, v0
	v_mov_b32_e32 v104, v0
	v_mov_b32_e32 v105, v0
	v_mov_b32_e32 v106, v0
	v_mov_b32_e32 v107, v0
	v_mov_b32_e32 v108, v0
	v_mov_b32_e32 v109, v0
	v_mov_b32_e32 v110, v0
	v_mov_b32_e32 v111, v0
	v_mov_b32_e32 v120, v0
	v_mov_b32_e32 v121, v0
	v_mov_b32_e32 v122, v0
	v_mov_b32_e32 v123, v0
	v_mov_b32_e32 v124, v0
	v_mov_b32_e32 v125, v0
	v_mov_b32_e32 v126, v0
	v_mov_b32_e32 v127, v0
	.p2align	6
